# GEMM1 epilogue: gelu_tanh chains regenerated with packed f32 ops (same operations and order, bit-identical), two elements per instruction
# speedup vs baseline: 1.0981x; 1.0029x over previous
; __device__ __forceinline__ float gelu_tanh(float x) { const float u = 1.5957691216f * (x + 0.044715f * x * x * x); return x * __builtin_amdgcn_rcpf(1.f + __expf(-u)); }
; __device__ __forceinline__ void st_bf16x8(bf16_t* p, const f32x4 a, const f32x4 b) { uint4 o; o.x = cvt_pk_bf16(a[0], a[1]); o.y = cvt_pk_bf16(a[2], a[3]); o.z = cvt_pk_bf16(b[0], b[1]); o.w = cvt_pk_bf16(b[2], b[3]); *(uint4*)p = o; }
;     __device__ __forceinline__ void row(const f32x4 (&a)[2][2], int row, int pn, int wc, int fq) const {
;     ...
;             const int head = (pn - 2) * 4 + wc;
;             f32x4 g[2][2]; float ss = 0.f;
; #pragma unroll
;             for (int bj = 0; bj < 2; ++bj)
; #pragma unroll
;                 for (int n = 0; n < 2; ++n)
; #pragma unroll
;                     for (int j = 0; j < 4; ++j) { const float t = gelu_tanh(a[bj][n][j]); g[bj][n][j] = t; ss += t * t; }
;             ss += __shfl_xor(ss, 16); ss += __shfl_xor(ss, 32);
;             const float rs = rsqrtf(ss * (1.f / 64.f) + EPS);
; #pragma unroll
;             for (int bj = 0; bj < 2; ++bj) { const int d = head * 64 + bj * 32 + 8 * fq;
;                 const f32x4 v0 = g[bj][0] * rs * *(const f32x4*)(g_v + d), v1 = g[bj][1] * rs * *(const f32x4*)(g_v + d + 4);
;                 st_bf16x8(pV + (size_t)row * 512 + d, v0, v1);
;                 if (row >= NP && row < NTOK) { float* o = out + O_VS + (size_t)(row - NP) * 512 + d; *(f32x4*)o = v0; *(f32x4*)(o + 4) = v1; } }
.LBB0_218:
	s_andn2_b64 vcc, exec, s[0:1]
	s_cbranch_vccnz .LBB0_223
	v_mov_b32_e32 v190, 0x3d372713
	v_mov_b32_e32 v192, 0xbfcc422a
	v_mov_b32_e32 v194, 0x3fb8aa3b
	v_pk_mul_f32 v[128:129], v[124:125], v[190:191] op_sel_hi:[1,0]
	v_pk_mul_f32 v[132:133], v[126:127], v[190:191] op_sel_hi:[1,0]
	v_pk_mul_f32 v[158:159], v[120:121], v[190:191] op_sel_hi:[1,0]
	v_pk_mul_f32 v[160:161], v[122:123], v[190:191] op_sel_hi:[1,0]
	v_pk_mul_f32 v[162:163], v[116:117], v[190:191] op_sel_hi:[1,0]
	v_pk_mul_f32 v[164:165], v[118:119], v[190:191] op_sel_hi:[1,0]
	v_pk_mul_f32 v[166:167], v[112:113], v[190:191] op_sel_hi:[1,0]
	v_pk_mul_f32 v[168:169], v[114:115], v[190:191] op_sel_hi:[1,0]
	v_pk_mul_f32 v[128:129], v[124:125], v[128:129]
	v_pk_mul_f32 v[132:133], v[126:127], v[132:133]
	v_pk_mul_f32 v[158:159], v[120:121], v[158:159]
	v_pk_mul_f32 v[160:161], v[122:123], v[160:161]
	v_pk_mul_f32 v[162:163], v[116:117], v[162:163]
	v_pk_mul_f32 v[164:165], v[118:119], v[164:165]
	v_pk_mul_f32 v[166:167], v[112:113], v[166:167]
	v_pk_mul_f32 v[168:169], v[114:115], v[168:169]
	v_pk_fma_f32 v[128:129], v[124:125], v[128:129], v[124:125]
	v_pk_fma_f32 v[132:133], v[126:127], v[132:133], v[126:127]
	v_pk_fma_f32 v[158:159], v[120:121], v[158:159], v[120:121]
	v_pk_fma_f32 v[160:161], v[122:123], v[160:161], v[122:123]
	v_pk_fma_f32 v[162:163], v[116:117], v[162:163], v[116:117]
	v_pk_fma_f32 v[164:165], v[118:119], v[164:165], v[118:119]
	v_pk_fma_f32 v[166:167], v[112:113], v[166:167], v[112:113]
	v_pk_fma_f32 v[168:169], v[114:115], v[168:169], v[114:115]
	v_pk_mul_f32 v[128:129], v[128:129], v[192:193] op_sel_hi:[1,0]
	v_pk_mul_f32 v[132:133], v[132:133], v[192:193] op_sel_hi:[1,0]
	v_pk_mul_f32 v[158:159], v[158:159], v[192:193] op_sel_hi:[1,0]
	v_pk_mul_f32 v[160:161], v[160:161], v[192:193] op_sel_hi:[1,0]
	v_pk_mul_f32 v[162:163], v[162:163], v[192:193] op_sel_hi:[1,0]
	v_pk_mul_f32 v[164:165], v[164:165], v[192:193] op_sel_hi:[1,0]
	v_pk_mul_f32 v[166:167], v[166:167], v[192:193] op_sel_hi:[1,0]
	v_pk_mul_f32 v[168:169], v[168:169], v[192:193] op_sel_hi:[1,0]
	v_pk_mul_f32 v[128:129], v[128:129], v[194:195] op_sel_hi:[1,0]
	v_pk_mul_f32 v[132:133], v[132:133], v[194:195] op_sel_hi:[1,0]
	v_pk_mul_f32 v[158:159], v[158:159], v[194:195] op_sel_hi:[1,0]
	v_pk_mul_f32 v[160:161], v[160:161], v[194:195] op_sel_hi:[1,0]
	v_pk_mul_f32 v[162:163], v[162:163], v[194:195] op_sel_hi:[1,0]
	v_pk_mul_f32 v[164:165], v[164:165], v[194:195] op_sel_hi:[1,0]
	v_pk_mul_f32 v[166:167], v[166:167], v[194:195] op_sel_hi:[1,0]
	v_pk_mul_f32 v[168:169], v[168:169], v[194:195] op_sel_hi:[1,0]
	v_exp_f32_e32 v128, v128
	v_exp_f32_e32 v129, v129
	v_exp_f32_e32 v132, v132
	v_exp_f32_e32 v133, v133
	v_exp_f32_e32 v158, v158
	v_exp_f32_e32 v159, v159
	v_exp_f32_e32 v160, v160
	v_exp_f32_e32 v161, v161
	v_exp_f32_e32 v162, v162
	v_exp_f32_e32 v163, v163
	v_exp_f32_e32 v164, v164
	v_exp_f32_e32 v165, v165
	v_exp_f32_e32 v166, v166
	v_exp_f32_e32 v167, v167
	v_exp_f32_e32 v168, v168
	v_exp_f32_e32 v169, v169
	v_pk_add_f32 v[128:129], v[128:129], 1.0 op_sel_hi:[1,0]
	v_pk_add_f32 v[132:133], v[132:133], 1.0 op_sel_hi:[1,0]
	v_pk_add_f32 v[158:159], v[158:159], 1.0 op_sel_hi:[1,0]
	v_pk_add_f32 v[160:161], v[160:161], 1.0 op_sel_hi:[1,0]
	v_pk_add_f32 v[162:163], v[162:163], 1.0 op_sel_hi:[1,0]
	v_pk_add_f32 v[164:165], v[164:165], 1.0 op_sel_hi:[1,0]
	v_pk_add_f32 v[166:167], v[166:167], 1.0 op_sel_hi:[1,0]
	v_pk_add_f32 v[168:169], v[168:169], 1.0 op_sel_hi:[1,0]
	v_rcp_f32_e32 v128, v128
	v_rcp_f32_e32 v129, v129
	v_rcp_f32_e32 v132, v132
	v_rcp_f32_e32 v133, v133
	v_rcp_f32_e32 v158, v158
	v_rcp_f32_e32 v159, v159
	v_rcp_f32_e32 v160, v160
	v_rcp_f32_e32 v161, v161
	v_rcp_f32_e32 v162, v162
	v_rcp_f32_e32 v163, v163
	v_rcp_f32_e32 v164, v164
	v_rcp_f32_e32 v165, v165
	v_rcp_f32_e32 v166, v166
	v_rcp_f32_e32 v167, v167
	v_rcp_f32_e32 v168, v168
	v_rcp_f32_e32 v169, v169
	v_pk_mul_f32 v[128:129], v[124:125], v[128:129]
	v_pk_mul_f32 v[132:133], v[126:127], v[132:133]
	v_pk_mul_f32 v[158:159], v[120:121], v[158:159]
	v_pk_mul_f32 v[160:161], v[122:123], v[160:161]
	v_pk_mul_f32 v[162:163], v[116:117], v[162:163]
	v_pk_mul_f32 v[164:165], v[118:119], v[164:165]
	v_pk_mul_f32 v[166:167], v[112:113], v[166:167]
	v_pk_mul_f32 v[168:169], v[114:115], v[168:169]
	v_pk_mul_f32 v[130:131], v[128:129], v[128:129]
	v_pk_mul_f32 v[134:135], v[132:133], v[132:133]
	v_add_f32_e32 v130, v130, v131
	v_add_f32_e32 v130, v134, v130
	v_pk_mul_f32 v[170:171], v[158:159], v[158:159]
	v_add_f32_e32 v130, v135, v130
	v_add_f32_e32 v130, v170, v130
	v_pk_mul_f32 v[172:173], v[160:161], v[160:161]
	v_add_f32_e32 v130, v171, v130
	v_add_f32_e32 v130, v172, v130
	v_pk_mul_f32 v[174:175], v[162:163], v[162:163]
	v_add_f32_e32 v130, v173, v130
	v_add_f32_e32 v130, v130, v174
	v_pk_mul_f32 v[176:177], v[164:165], v[164:165]
	v_add_f32_e32 v130, v175, v130
	v_add_f32_e32 v130, v176, v130
	v_pk_mul_f32 v[178:179], v[166:167], v[166:167]
	v_add_f32_e32 v130, v177, v130
	v_add_f32_e32 v130, v178, v130
	v_pk_mul_f32 v[180:181], v[168:169], v[168:169]
	v_add_f32_e32 v130, v179, v130
	v_add_f32_e32 v130, v180, v130
	v_add_f32_e32 v130, v181, v130
	ds_bpermute_b32 v131, v229, v130
	v_lshl_add_u64 v[180:181], v[140:141], 2, s[18:19]
	v_ashrrev_i32_e32 v157, 31, v156
	v_lshlrev_b64 v[174:175], 10, v[156:157]
	v_lshlrev_b32_e32 v172, 9, v156
	s_waitcnt lgkmcnt(0)
	v_add_f32_e32 v130, v130, v131
	ds_bpermute_b32 v131, v230, v130
	v_mov_b32_e32 v173, v141
	v_cndmask_b32_e64 v157, 0, 1, s[10:11]
	v_cmp_ne_u32_e64 s[0:1], 1, v157
	s_waitcnt lgkmcnt(0)
	v_add_f32_e32 v130, v130, v131
	v_fmamk_f32 v130, v130, 0x3c800000, v188
	v_cmp_gt_f32_e32 vcc, s13, v130
	v_mul_f32_e32 v131, 0x4b800000, v130
	s_nop 0
	v_cndmask_b32_e32 v130, v130, v131, vcc
	v_rsq_f32_e32 v130, v130
	s_nop 0
	v_mul_f32_e32 v131, 0x45800000, v130
	v_cndmask_b32_e32 v170, v130, v131, vcc
	v_pk_mul_f32 v[176:177], v[128:129], v[170:171] op_sel_hi:[1,0]
	v_pk_mul_f32 v[178:179], v[132:133], v[170:171] op_sel_hi:[1,0]
	global_load_dwordx4 v[128:131], v[180:181], off offset:16
	global_load_dwordx4 v[132:135], v[180:181], off
	v_pk_mul_f32 v[158:159], v[158:159], v[170:171] op_sel_hi:[1,0]
	v_pk_mul_f32 v[160:161], v[160:161], v[170:171] op_sel_hi:[1,0]
	s_andn2_b64 vcc, exec, s[10:11]
	s_waitcnt vmcnt(0)
	v_pk_mul_f32 v[128:129], v[128:129], v[158:159]
	v_lshl_add_u64 v[158:159], s[46:47], 0, v[174:175]
	v_pk_mul_f32 v[134:135], v[134:135], v[178:179]
	v_pk_mul_f32 v[132:133], v[132:133], v[176:177]
	v_pk_mul_f32 v[130:131], v[130:131], v[160:161]
	v_lshl_add_u64 v[158:159], v[140:141], 1, v[158:159]
	v_lshl_add_u64 v[160:161], v[172:173], 2, s[56:57]
	v_cvt_pk_bf16_f32 v174, v132, v133
	v_cvt_pk_bf16_f32 v175, v134, v135
	v_cvt_pk_bf16_f32 v176, v128, v129
	v_cvt_pk_bf16_f32 v177, v130, v131
	global_store_dwordx4 v[158:159], v[174:177], off
	s_cbranch_vccnz .LBB0_221
;     __device__ __forceinline__ void row(const f32x4 (&a)[2][2], int row, int pn, int wc, int fq) const {
;     ...
;                 if (row >= NP && row < NTOK) { float* o = out + O_VS + (size_t)(row - NP) * 512 + d; *(f32x4*)o = v0; *(f32x4*)(o + 4) = v1; } }
	v_lshl_add_u64 v[172:173], v[140:141], 2, v[160:161]
	v_lshl_add_u64 v[174:175], v[172:173], 0, s[70:71]
	v_add_co_u32_e32 v172, vcc, 0x2108000, v172
	s_nop 1
	v_addc_co_u32_e32 v173, vcc, 0, v173, vcc
	global_store_dwordx4 v[172:173], v[132:135], off
	global_store_dwordx4 v[174:175], v[128:131], off offset:16

; __device__ __forceinline__ float gelu_tanh(float x) { const float u = 1.5957691216f * (x + 0.044715f * x * x * x); return x * __builtin_amdgcn_rcpf(1.f + __expf(-u)); }
; __device__ __forceinline__ void st_bf16x8(bf16_t* p, const f32x4 a, const f32x4 b) { uint4 o; o.x = cvt_pk_bf16(a[0], a[1]); o.y = cvt_pk_bf16(a[2], a[3]); o.z = cvt_pk_bf16(b[0], b[1]); o.w = cvt_pk_bf16(b[2], b[3]); *(uint4*)p = o; }
;     __device__ __forceinline__ void row(const f32x4 (&a)[2][2], int row, int pn, int wc, int fq) const {
;         if (pn < 2 || pn == 4 || pn == 5) {
;             bf16_t* dst = (pn < 2 ? pU : pBG) + (size_t)row * 512 + (pn & 1) * 256 + wc * 32 + 8 * fq;
; #pragma unroll
;             for (int bj = 0; bj < 2; ++bj) { f32x4 v0 = a[bj][0], v1 = a[bj][1];
;                 if (pn < 2) {
; #pragma unroll
;                     for (int j = 0; j < 4; ++j) { v0[j] = gelu_tanh(v0[j]); v1[j] = gelu_tanh(v1[j]); } }
;                 st_bf16x8(dst + bj * HALF, v0, v1); }
.LBB0_224:
	v_cndmask_b32_e64 v128, 0, 1, s[80:81]
	s_and_b32 s61, s4, 0x100
	s_andn2_b64 vcc, exec, s[0:1]
	v_cmp_ne_u32_e64 s[4:5], 1, v128
	s_cbranch_vccnz .LBB0_230
	s_and_b64 vcc, exec, s[4:5]
	s_cbranch_vccnz .LBB0_227
	v_mov_b32_e32 v190, 0x3d372713
	v_mov_b32_e32 v192, 0xbfcc422a
	v_mov_b32_e32 v194, 0x3fb8aa3b
	v_pk_mul_f32 v[196:197], v[120:121], v[190:191] op_sel_hi:[1,0]
	v_pk_mul_f32 v[198:199], v[122:123], v[190:191] op_sel_hi:[1,0]
	v_pk_mul_f32 v[200:201], v[124:125], v[190:191] op_sel_hi:[1,0]
	v_pk_mul_f32 v[202:203], v[126:127], v[190:191] op_sel_hi:[1,0]
	v_pk_mul_f32 v[196:197], v[120:121], v[196:197]
	v_pk_mul_f32 v[198:199], v[122:123], v[198:199]
	v_pk_mul_f32 v[200:201], v[124:125], v[200:201]
	v_pk_mul_f32 v[202:203], v[126:127], v[202:203]
	v_pk_fma_f32 v[196:197], v[120:121], v[196:197], v[120:121]
	v_pk_fma_f32 v[198:199], v[122:123], v[198:199], v[122:123]
	v_pk_fma_f32 v[200:201], v[124:125], v[200:201], v[124:125]
	v_pk_fma_f32 v[202:203], v[126:127], v[202:203], v[126:127]
	v_pk_mul_f32 v[196:197], v[196:197], v[192:193] op_sel_hi:[1,0]
	v_pk_mul_f32 v[198:199], v[198:199], v[192:193] op_sel_hi:[1,0]
	v_pk_mul_f32 v[200:201], v[200:201], v[192:193] op_sel_hi:[1,0]
	v_pk_mul_f32 v[202:203], v[202:203], v[192:193] op_sel_hi:[1,0]
	v_pk_mul_f32 v[196:197], v[196:197], v[194:195] op_sel_hi:[1,0]
	v_pk_mul_f32 v[198:199], v[198:199], v[194:195] op_sel_hi:[1,0]
	v_pk_mul_f32 v[200:201], v[200:201], v[194:195] op_sel_hi:[1,0]
	v_pk_mul_f32 v[202:203], v[202:203], v[194:195] op_sel_hi:[1,0]
	v_exp_f32_e32 v196, v196
	v_exp_f32_e32 v197, v197
	v_exp_f32_e32 v198, v198
	v_exp_f32_e32 v199, v199
	v_exp_f32_e32 v200, v200
	v_exp_f32_e32 v201, v201
	v_exp_f32_e32 v202, v202
	v_exp_f32_e32 v203, v203
	v_pk_add_f32 v[196:197], v[196:197], 1.0 op_sel_hi:[1,0]
	v_pk_add_f32 v[198:199], v[198:199], 1.0 op_sel_hi:[1,0]
	v_pk_add_f32 v[200:201], v[200:201], 1.0 op_sel_hi:[1,0]
	v_pk_add_f32 v[202:203], v[202:203], 1.0 op_sel_hi:[1,0]
	v_rcp_f32_e32 v196, v196
	v_rcp_f32_e32 v197, v197
	v_rcp_f32_e32 v198, v198
	v_rcp_f32_e32 v199, v199
	v_rcp_f32_e32 v200, v200
	v_rcp_f32_e32 v201, v201
	v_rcp_f32_e32 v202, v202
	v_rcp_f32_e32 v203, v203
	v_pk_mul_f32 v[120:121], v[120:121], v[196:197]
	v_pk_mul_f32 v[122:123], v[122:123], v[198:199]
	v_pk_mul_f32 v[124:125], v[124:125], v[200:201]
	v_pk_mul_f32 v[126:127], v[126:127], v[202:203]
	s_nop 0
	s_nop 0
	s_nop 0
	s_nop 0
.LBB0_227:
	s_and_b64 s[0:1], s[80:81], exec
	v_ashrrev_i32_e32 v157, 31, v156
	s_cselect_b32 s1, s31, s49
	s_cselect_b32 s0, s30, s48
	v_lshlrev_b64 v[128:129], 10, v[156:157]
	v_lshl_add_u64 v[128:129], s[0:1], 0, v[128:129]
	s_lshl_b32 s64, s61, 1
	v_lshl_add_u64 v[128:129], v[128:129], 0, s[64:65]
	s_lshl_b32 s64, s91, 1
	v_lshl_add_u64 v[128:129], v[128:129], 0, s[64:65]
	v_lshlrev_b32_e32 v130, 1, v142
	v_mov_b32_e32 v131, v141
	v_lshl_add_u64 v[128:129], v[128:129], 0, v[130:131]
	s_and_b64 vcc, exec, s[4:5]
	v_cvt_pk_bf16_f32 v124, v124, v125
	v_cvt_pk_bf16_f32 v125, v126, v127
	v_cvt_pk_bf16_f32 v126, v120, v121
	v_cvt_pk_bf16_f32 v127, v122, v123
	global_store_dwordx4 v[128:129], v[124:127], off
	s_cbranch_vccnz .LBB0_229
	v_mov_b32_e32 v190, 0x3d372713
	v_mov_b32_e32 v192, 0xbfcc422a
	v_mov_b32_e32 v194, 0x3fb8aa3b
	v_pk_mul_f32 v[196:197], v[112:113], v[190:191] op_sel_hi:[1,0]
	v_pk_mul_f32 v[198:199], v[114:115], v[190:191] op_sel_hi:[1,0]
	v_pk_mul_f32 v[200:201], v[116:117], v[190:191] op_sel_hi:[1,0]
	v_pk_mul_f32 v[202:203], v[118:119], v[190:191] op_sel_hi:[1,0]
	v_pk_mul_f32 v[196:197], v[112:113], v[196:197]
	v_pk_mul_f32 v[198:199], v[114:115], v[198:199]
	v_pk_mul_f32 v[200:201], v[116:117], v[200:201]
	v_pk_mul_f32 v[202:203], v[118:119], v[202:203]
	v_pk_fma_f32 v[196:197], v[112:113], v[196:197], v[112:113]
	v_pk_fma_f32 v[198:199], v[114:115], v[198:199], v[114:115]
	v_pk_fma_f32 v[200:201], v[116:117], v[200:201], v[116:117]
	v_pk_fma_f32 v[202:203], v[118:119], v[202:203], v[118:119]
	v_pk_mul_f32 v[196:197], v[196:197], v[192:193] op_sel_hi:[1,0]
	v_pk_mul_f32 v[198:199], v[198:199], v[192:193] op_sel_hi:[1,0]
	v_pk_mul_f32 v[200:201], v[200:201], v[192:193] op_sel_hi:[1,0]
	v_pk_mul_f32 v[202:203], v[202:203], v[192:193] op_sel_hi:[1,0]
	v_pk_mul_f32 v[196:197], v[196:197], v[194:195] op_sel_hi:[1,0]
	v_pk_mul_f32 v[198:199], v[198:199], v[194:195] op_sel_hi:[1,0]
	v_pk_mul_f32 v[200:201], v[200:201], v[194:195] op_sel_hi:[1,0]
	v_pk_mul_f32 v[202:203], v[202:203], v[194:195] op_sel_hi:[1,0]
	v_exp_f32_e32 v196, v196
	v_exp_f32_e32 v197, v197
	v_exp_f32_e32 v198, v198
	v_exp_f32_e32 v199, v199
	v_exp_f32_e32 v200, v200
	v_exp_f32_e32 v201, v201
	v_exp_f32_e32 v202, v202
	v_exp_f32_e32 v203, v203
	v_pk_add_f32 v[196:197], v[196:197], 1.0 op_sel_hi:[1,0]
	v_pk_add_f32 v[198:199], v[198:199], 1.0 op_sel_hi:[1,0]
	v_pk_add_f32 v[200:201], v[200:201], 1.0 op_sel_hi:[1,0]
	v_pk_add_f32 v[202:203], v[202:203], 1.0 op_sel_hi:[1,0]
	v_rcp_f32_e32 v196, v196
	v_rcp_f32_e32 v197, v197
	v_rcp_f32_e32 v198, v198
	v_rcp_f32_e32 v199, v199
	v_rcp_f32_e32 v200, v200
	v_rcp_f32_e32 v201, v201
	v_rcp_f32_e32 v202, v202
	v_rcp_f32_e32 v203, v203
	v_pk_mul_f32 v[112:113], v[112:113], v[196:197]
	v_pk_mul_f32 v[114:115], v[114:115], v[198:199]
	v_pk_mul_f32 v[116:117], v[116:117], v[200:201]
	v_pk_mul_f32 v[118:119], v[118:119], v[202:203]
	s_nop 0
	s_nop 0
	s_nop 0
	s_nop 0

; __device__ __forceinline__ float gelu_tanh(float x) { const float u = 1.5957691216f * (x + 0.044715f * x * x * x); return x * __builtin_amdgcn_rcpf(1.f + __expf(-u)); }
; __device__ __forceinline__ void st_bf16x8(bf16_t* p, const f32x4 a, const f32x4 b) { uint4 o; o.x = cvt_pk_bf16(a[0], a[1]); o.y = cvt_pk_bf16(a[2], a[3]); o.z = cvt_pk_bf16(b[0], b[1]); o.w = cvt_pk_bf16(b[2], b[3]); *(uint4*)p = o; }
;     __device__ __forceinline__ void row(const f32x4 (&a)[2][2], int row, int pn, int wc, int fq) const {
;     ...
;             const int head = (pn - 2) * 4 + wc;
;             f32x4 g[2][2]; float ss = 0.f;
; #pragma unroll
;             for (int bj = 0; bj < 2; ++bj)
; #pragma unroll
;                 for (int n = 0; n < 2; ++n)
; #pragma unroll
;                     for (int j = 0; j < 4; ++j) { const float t = gelu_tanh(a[bj][n][j]); g[bj][n][j] = t; ss += t * t; }
;             ss += __shfl_xor(ss, 16); ss += __shfl_xor(ss, 32);
;             const float rs = rsqrtf(ss * (1.f / 64.f) + EPS);
; #pragma unroll
;             for (int bj = 0; bj < 2; ++bj) { const int d = head * 64 + bj * 32 + 8 * fq;
;                 const f32x4 v0 = g[bj][0] * rs * *(const f32x4*)(g_v + d), v1 = g[bj][1] * rs * *(const f32x4*)(g_v + d + 4);
;                 st_bf16x8(pV + (size_t)row * 512 + d, v0, v1);
;                 if (row >= NP && row < NTOK) { float* o = out + O_VS + (size_t)(row - NP) * 512 + d; *(f32x4*)o = v0; *(f32x4*)(o + 4) = v1; } }
.LBB0_240:
	s_andn2_b64 vcc, exec, s[0:1]
	s_cbranch_vccnz .LBB0_245
	v_mov_b32_e32 v190, 0x3d372713
	v_mov_b32_e32 v192, 0xbfcc422a
	v_mov_b32_e32 v194, 0x3fb8aa3b
	v_pk_mul_f32 v[112:113], v[108:109], v[190:191] op_sel_hi:[1,0]
	v_pk_mul_f32 v[116:117], v[110:111], v[190:191] op_sel_hi:[1,0]
	v_pk_mul_f32 v[122:123], v[104:105], v[190:191] op_sel_hi:[1,0]
	v_pk_mul_f32 v[124:125], v[106:107], v[190:191] op_sel_hi:[1,0]
	v_pk_mul_f32 v[126:127], v[100:101], v[190:191] op_sel_hi:[1,0]
	v_pk_mul_f32 v[128:129], v[102:103], v[190:191] op_sel_hi:[1,0]
	v_pk_mul_f32 v[130:131], v[96:97], v[190:191] op_sel_hi:[1,0]
	v_pk_mul_f32 v[132:133], v[98:99], v[190:191] op_sel_hi:[1,0]
	v_pk_mul_f32 v[112:113], v[108:109], v[112:113]
	v_pk_mul_f32 v[116:117], v[110:111], v[116:117]
	v_pk_mul_f32 v[122:123], v[104:105], v[122:123]
	v_pk_mul_f32 v[124:125], v[106:107], v[124:125]
	v_pk_mul_f32 v[126:127], v[100:101], v[126:127]
	v_pk_mul_f32 v[128:129], v[102:103], v[128:129]
	v_pk_mul_f32 v[130:131], v[96:97], v[130:131]
	v_pk_mul_f32 v[132:133], v[98:99], v[132:133]
	v_pk_fma_f32 v[112:113], v[108:109], v[112:113], v[108:109]
	v_pk_fma_f32 v[116:117], v[110:111], v[116:117], v[110:111]
	v_pk_fma_f32 v[122:123], v[104:105], v[122:123], v[104:105]
	v_pk_fma_f32 v[124:125], v[106:107], v[124:125], v[106:107]
	v_pk_fma_f32 v[126:127], v[100:101], v[126:127], v[100:101]
	v_pk_fma_f32 v[128:129], v[102:103], v[128:129], v[102:103]
	v_pk_fma_f32 v[130:131], v[96:97], v[130:131], v[96:97]
	v_pk_fma_f32 v[132:133], v[98:99], v[132:133], v[98:99]
	v_pk_mul_f32 v[112:113], v[112:113], v[192:193] op_sel_hi:[1,0]
	v_pk_mul_f32 v[116:117], v[116:117], v[192:193] op_sel_hi:[1,0]
	v_pk_mul_f32 v[122:123], v[122:123], v[192:193] op_sel_hi:[1,0]
	v_pk_mul_f32 v[124:125], v[124:125], v[192:193] op_sel_hi:[1,0]
	v_pk_mul_f32 v[126:127], v[126:127], v[192:193] op_sel_hi:[1,0]
	v_pk_mul_f32 v[128:129], v[128:129], v[192:193] op_sel_hi:[1,0]
	v_pk_mul_f32 v[130:131], v[130:131], v[192:193] op_sel_hi:[1,0]
	v_pk_mul_f32 v[132:133], v[132:133], v[192:193] op_sel_hi:[1,0]
	v_pk_mul_f32 v[112:113], v[112:113], v[194:195] op_sel_hi:[1,0]
	v_pk_mul_f32 v[116:117], v[116:117], v[194:195] op_sel_hi:[1,0]
	v_pk_mul_f32 v[122:123], v[122:123], v[194:195] op_sel_hi:[1,0]
	v_pk_mul_f32 v[124:125], v[124:125], v[194:195] op_sel_hi:[1,0]
	v_pk_mul_f32 v[126:127], v[126:127], v[194:195] op_sel_hi:[1,0]
	v_pk_mul_f32 v[128:129], v[128:129], v[194:195] op_sel_hi:[1,0]
	v_pk_mul_f32 v[130:131], v[130:131], v[194:195] op_sel_hi:[1,0]
	v_pk_mul_f32 v[132:133], v[132:133], v[194:195] op_sel_hi:[1,0]
	v_exp_f32_e32 v112, v112
	v_exp_f32_e32 v113, v113
	v_exp_f32_e32 v116, v116
	v_exp_f32_e32 v117, v117
	v_exp_f32_e32 v122, v122
	v_exp_f32_e32 v123, v123
	v_exp_f32_e32 v124, v124
	v_exp_f32_e32 v125, v125
	v_exp_f32_e32 v126, v126
	v_exp_f32_e32 v127, v127
	v_exp_f32_e32 v128, v128
	v_exp_f32_e32 v129, v129
	v_exp_f32_e32 v130, v130
	v_exp_f32_e32 v131, v131
	v_exp_f32_e32 v132, v132
	v_exp_f32_e32 v133, v133
	v_pk_add_f32 v[112:113], v[112:113], 1.0 op_sel_hi:[1,0]
	v_pk_add_f32 v[116:117], v[116:117], 1.0 op_sel_hi:[1,0]
	v_pk_add_f32 v[122:123], v[122:123], 1.0 op_sel_hi:[1,0]
	v_pk_add_f32 v[124:125], v[124:125], 1.0 op_sel_hi:[1,0]
	v_pk_add_f32 v[126:127], v[126:127], 1.0 op_sel_hi:[1,0]
	v_pk_add_f32 v[128:129], v[128:129], 1.0 op_sel_hi:[1,0]
	v_pk_add_f32 v[130:131], v[130:131], 1.0 op_sel_hi:[1,0]
	v_pk_add_f32 v[132:133], v[132:133], 1.0 op_sel_hi:[1,0]
	v_rcp_f32_e32 v112, v112
	v_rcp_f32_e32 v113, v113
	v_rcp_f32_e32 v116, v116
	v_rcp_f32_e32 v117, v117
	v_rcp_f32_e32 v122, v122
	v_rcp_f32_e32 v123, v123
	v_rcp_f32_e32 v124, v124
	v_rcp_f32_e32 v125, v125
	v_rcp_f32_e32 v126, v126
	v_rcp_f32_e32 v127, v127
	v_rcp_f32_e32 v128, v128
	v_rcp_f32_e32 v129, v129
	v_rcp_f32_e32 v130, v130
	v_rcp_f32_e32 v131, v131
	v_rcp_f32_e32 v132, v132
	v_rcp_f32_e32 v133, v133
	v_pk_mul_f32 v[112:113], v[108:109], v[112:113]
	v_pk_mul_f32 v[116:117], v[110:111], v[116:117]
	v_pk_mul_f32 v[122:123], v[104:105], v[122:123]
	v_pk_mul_f32 v[124:125], v[106:107], v[124:125]
	v_pk_mul_f32 v[126:127], v[100:101], v[126:127]
	v_pk_mul_f32 v[128:129], v[102:103], v[128:129]
	v_pk_mul_f32 v[130:131], v[96:97], v[130:131]
	v_pk_mul_f32 v[132:133], v[98:99], v[132:133]
	v_pk_mul_f32 v[114:115], v[112:113], v[112:113]
	v_pk_mul_f32 v[118:119], v[116:117], v[116:117]
	v_add_f32_e32 v114, v114, v115
	v_add_f32_e32 v114, v118, v114
	v_pk_mul_f32 v[134:135], v[122:123], v[122:123]
	v_add_f32_e32 v114, v119, v114
	v_add_f32_e32 v114, v134, v114
	v_pk_mul_f32 v[158:159], v[124:125], v[124:125]
	v_add_f32_e32 v114, v135, v114
	v_add_f32_e32 v114, v158, v114
	v_pk_mul_f32 v[160:161], v[126:127], v[126:127]
	v_add_f32_e32 v114, v159, v114
	v_add_f32_e32 v114, v114, v160
	v_pk_mul_f32 v[162:163], v[128:129], v[128:129]
	v_add_f32_e32 v114, v161, v114
	v_add_f32_e32 v114, v162, v114
	v_pk_mul_f32 v[164:165], v[130:131], v[130:131]
	v_add_f32_e32 v114, v163, v114
	v_add_f32_e32 v114, v164, v114
	v_pk_mul_f32 v[166:167], v[132:133], v[132:133]
	v_add_f32_e32 v114, v165, v114
	v_add_f32_e32 v114, v166, v114
	v_add_f32_e32 v114, v167, v114
	ds_bpermute_b32 v115, v229, v114
	v_lshl_add_u64 v[166:167], v[140:141], 2, s[18:19]
	v_ashrrev_i32_e32 v121, 31, v120
	v_lshlrev_b64 v[160:161], 10, v[120:121]
	v_lshlrev_b32_e32 v158, 9, v120
	s_waitcnt lgkmcnt(0)
	v_add_f32_e32 v114, v114, v115
	ds_bpermute_b32 v115, v230, v114
	v_mov_b32_e32 v159, v141
	v_cndmask_b32_e64 v121, 0, 1, s[10:11]
	v_cmp_ne_u32_e64 s[0:1], 1, v121
	s_waitcnt lgkmcnt(0)
	v_add_f32_e32 v114, v114, v115
	v_fmamk_f32 v114, v114, 0x3c800000, v188
	v_cmp_gt_f32_e32 vcc, s13, v114
	v_mul_f32_e32 v115, 0x4b800000, v114
	s_nop 0
	v_cndmask_b32_e32 v114, v114, v115, vcc
	v_rsq_f32_e32 v114, v114
	s_nop 0
	v_mul_f32_e32 v115, 0x45800000, v114
	v_cndmask_b32_e32 v134, v114, v115, vcc
	v_pk_mul_f32 v[162:163], v[112:113], v[134:135] op_sel_hi:[1,0]
	v_pk_mul_f32 v[164:165], v[116:117], v[134:135] op_sel_hi:[1,0]
	global_load_dwordx4 v[112:115], v[166:167], off offset:16
	global_load_dwordx4 v[116:119], v[166:167], off
	v_pk_mul_f32 v[122:123], v[122:123], v[134:135] op_sel_hi:[1,0]
	v_pk_mul_f32 v[124:125], v[124:125], v[134:135] op_sel_hi:[1,0]
	s_andn2_b64 vcc, exec, s[10:11]
	s_waitcnt vmcnt(0)
	v_pk_mul_f32 v[112:113], v[112:113], v[122:123]
	v_lshl_add_u64 v[122:123], s[46:47], 0, v[160:161]
	v_pk_mul_f32 v[118:119], v[118:119], v[164:165]
	v_pk_mul_f32 v[116:117], v[116:117], v[162:163]
	v_pk_mul_f32 v[114:115], v[114:115], v[124:125]
	v_lshl_add_u64 v[122:123], v[140:141], 1, v[122:123]
	v_lshl_add_u64 v[124:125], v[158:159], 2, s[56:57]
	v_cvt_pk_bf16_f32 v160, v116, v117
	v_cvt_pk_bf16_f32 v161, v118, v119
	v_cvt_pk_bf16_f32 v162, v112, v113
	v_cvt_pk_bf16_f32 v163, v114, v115
	global_store_dwordx4 v[122:123], v[160:163], off
	s_cbranch_vccnz .LBB0_243
;     __device__ __forceinline__ void row(const f32x4 (&a)[2][2], int row, int pn, int wc, int fq) const {
;     ...
;                 if (row >= NP && row < NTOK) { float* o = out + O_VS + (size_t)(row - NP) * 512 + d; *(f32x4*)o = v0; *(f32x4*)(o + 4) = v1; } }
	v_lshl_add_u64 v[158:159], v[140:141], 2, v[124:125]
	v_lshl_add_u64 v[160:161], v[158:159], 0, s[70:71]
	v_add_co_u32_e32 v158, vcc, 0x2108000, v158
	s_nop 1
	v_addc_co_u32_e32 v159, vcc, 0, v159, vcc
	global_store_dwordx4 v[158:159], v[116:119], off
	global_store_dwordx4 v[160:161], v[112:115], off offset:16

; __device__ __forceinline__ float gelu_tanh(float x) { const float u = 1.5957691216f * (x + 0.044715f * x * x * x); return x * __builtin_amdgcn_rcpf(1.f + __expf(-u)); }
; __device__ __forceinline__ void st_bf16x8(bf16_t* p, const f32x4 a, const f32x4 b) { uint4 o; o.x = cvt_pk_bf16(a[0], a[1]); o.y = cvt_pk_bf16(a[2], a[3]); o.z = cvt_pk_bf16(b[0], b[1]); o.w = cvt_pk_bf16(b[2], b[3]); *(uint4*)p = o; }
;     __device__ __forceinline__ void row(const f32x4 (&a)[2][2], int row, int pn, int wc, int fq) const {
;         if (pn < 2 || pn == 4 || pn == 5) {
;             bf16_t* dst = (pn < 2 ? pU : pBG) + (size_t)row * 512 + (pn & 1) * 256 + wc * 32 + 8 * fq;
; #pragma unroll
;             for (int bj = 0; bj < 2; ++bj) { f32x4 v0 = a[bj][0], v1 = a[bj][1];
;                 if (pn < 2) {
; #pragma unroll
;                     for (int j = 0; j < 4; ++j) { v0[j] = gelu_tanh(v0[j]); v1[j] = gelu_tanh(v1[j]); } }
;                 st_bf16x8(dst + bj * HALF, v0, v1); }
.LBB0_246:
	s_and_b64 vcc, exec, s[4:5]
	s_cbranch_vccnz .LBB0_248
	v_mov_b32_e32 v190, 0x3d372713
	v_mov_b32_e32 v192, 0xbfcc422a
	v_mov_b32_e32 v194, 0x3fb8aa3b
	v_pk_mul_f32 v[196:197], v[104:105], v[190:191] op_sel_hi:[1,0]
	v_pk_mul_f32 v[198:199], v[106:107], v[190:191] op_sel_hi:[1,0]
	v_pk_mul_f32 v[200:201], v[108:109], v[190:191] op_sel_hi:[1,0]
	v_pk_mul_f32 v[202:203], v[110:111], v[190:191] op_sel_hi:[1,0]
	v_pk_mul_f32 v[196:197], v[104:105], v[196:197]
	v_pk_mul_f32 v[198:199], v[106:107], v[198:199]
	v_pk_mul_f32 v[200:201], v[108:109], v[200:201]
	v_pk_mul_f32 v[202:203], v[110:111], v[202:203]
	v_pk_fma_f32 v[196:197], v[104:105], v[196:197], v[104:105]
	v_pk_fma_f32 v[198:199], v[106:107], v[198:199], v[106:107]
	v_pk_fma_f32 v[200:201], v[108:109], v[200:201], v[108:109]
	v_pk_fma_f32 v[202:203], v[110:111], v[202:203], v[110:111]
	v_pk_mul_f32 v[196:197], v[196:197], v[192:193] op_sel_hi:[1,0]
	v_pk_mul_f32 v[198:199], v[198:199], v[192:193] op_sel_hi:[1,0]
	v_pk_mul_f32 v[200:201], v[200:201], v[192:193] op_sel_hi:[1,0]
	v_pk_mul_f32 v[202:203], v[202:203], v[192:193] op_sel_hi:[1,0]
	v_pk_mul_f32 v[196:197], v[196:197], v[194:195] op_sel_hi:[1,0]
	v_pk_mul_f32 v[198:199], v[198:199], v[194:195] op_sel_hi:[1,0]
	v_pk_mul_f32 v[200:201], v[200:201], v[194:195] op_sel_hi:[1,0]
	v_pk_mul_f32 v[202:203], v[202:203], v[194:195] op_sel_hi:[1,0]
	v_exp_f32_e32 v196, v196
	v_exp_f32_e32 v197, v197
	v_exp_f32_e32 v198, v198
	v_exp_f32_e32 v199, v199
	v_exp_f32_e32 v200, v200
	v_exp_f32_e32 v201, v201
	v_exp_f32_e32 v202, v202
	v_exp_f32_e32 v203, v203
	v_pk_add_f32 v[196:197], v[196:197], 1.0 op_sel_hi:[1,0]
	v_pk_add_f32 v[198:199], v[198:199], 1.0 op_sel_hi:[1,0]
	v_pk_add_f32 v[200:201], v[200:201], 1.0 op_sel_hi:[1,0]
	v_pk_add_f32 v[202:203], v[202:203], 1.0 op_sel_hi:[1,0]
	v_rcp_f32_e32 v196, v196
	v_rcp_f32_e32 v197, v197
	v_rcp_f32_e32 v198, v198
	v_rcp_f32_e32 v199, v199
	v_rcp_f32_e32 v200, v200
	v_rcp_f32_e32 v201, v201
	v_rcp_f32_e32 v202, v202
	v_rcp_f32_e32 v203, v203
	v_pk_mul_f32 v[104:105], v[104:105], v[196:197]
	v_pk_mul_f32 v[106:107], v[106:107], v[198:199]
	v_pk_mul_f32 v[108:109], v[108:109], v[200:201]
	v_pk_mul_f32 v[110:111], v[110:111], v[202:203]
	s_nop 0
	s_nop 0
	s_nop 0
	s_nop 0
.LBB0_248:
	s_and_b64 s[0:1], s[80:81], exec
	v_ashrrev_i32_e32 v121, 31, v120
	s_cselect_b32 s1, s31, s49
	s_cselect_b32 s0, s30, s48
	v_lshlrev_b64 v[112:113], 10, v[120:121]
	v_lshl_add_u64 v[112:113], s[0:1], 0, v[112:113]
	s_lshl_b32 s64, s61, 1
	v_lshl_add_u64 v[112:113], v[112:113], 0, s[64:65]
	s_lshl_b32 s64, s91, 1
	v_lshl_add_u64 v[112:113], v[112:113], 0, s[64:65]
	v_lshlrev_b32_e32 v114, 1, v142
	v_mov_b32_e32 v115, v141
	v_lshl_add_u64 v[112:113], v[112:113], 0, v[114:115]
	s_and_b64 vcc, exec, s[4:5]
	v_cvt_pk_bf16_f32 v108, v108, v109
	v_cvt_pk_bf16_f32 v109, v110, v111
	v_cvt_pk_bf16_f32 v110, v104, v105
	v_cvt_pk_bf16_f32 v111, v106, v107
	global_store_dwordx4 v[112:113], v[108:111], off
	s_cbranch_vccnz .LBB0_250
	v_mov_b32_e32 v190, 0x3d372713
	v_mov_b32_e32 v192, 0xbfcc422a
	v_mov_b32_e32 v194, 0x3fb8aa3b
	v_pk_mul_f32 v[196:197], v[96:97], v[190:191] op_sel_hi:[1,0]
	v_pk_mul_f32 v[198:199], v[98:99], v[190:191] op_sel_hi:[1,0]
	v_pk_mul_f32 v[200:201], v[100:101], v[190:191] op_sel_hi:[1,0]
	v_pk_mul_f32 v[202:203], v[102:103], v[190:191] op_sel_hi:[1,0]
	v_pk_mul_f32 v[196:197], v[96:97], v[196:197]
	v_pk_mul_f32 v[198:199], v[98:99], v[198:199]
	v_pk_mul_f32 v[200:201], v[100:101], v[200:201]
	v_pk_mul_f32 v[202:203], v[102:103], v[202:203]
	v_pk_fma_f32 v[196:197], v[96:97], v[196:197], v[96:97]
	v_pk_fma_f32 v[198:199], v[98:99], v[198:199], v[98:99]
	v_pk_fma_f32 v[200:201], v[100:101], v[200:201], v[100:101]
	v_pk_fma_f32 v[202:203], v[102:103], v[202:203], v[102:103]
	v_pk_mul_f32 v[196:197], v[196:197], v[192:193] op_sel_hi:[1,0]
	v_pk_mul_f32 v[198:199], v[198:199], v[192:193] op_sel_hi:[1,0]
	v_pk_mul_f32 v[200:201], v[200:201], v[192:193] op_sel_hi:[1,0]
	v_pk_mul_f32 v[202:203], v[202:203], v[192:193] op_sel_hi:[1,0]
	v_pk_mul_f32 v[196:197], v[196:197], v[194:195] op_sel_hi:[1,0]
	v_pk_mul_f32 v[198:199], v[198:199], v[194:195] op_sel_hi:[1,0]
	v_pk_mul_f32 v[200:201], v[200:201], v[194:195] op_sel_hi:[1,0]
	v_pk_mul_f32 v[202:203], v[202:203], v[194:195] op_sel_hi:[1,0]
	v_exp_f32_e32 v196, v196
	v_exp_f32_e32 v197, v197
	v_exp_f32_e32 v198, v198
	v_exp_f32_e32 v199, v199
	v_exp_f32_e32 v200, v200
	v_exp_f32_e32 v201, v201
	v_exp_f32_e32 v202, v202
	v_exp_f32_e32 v203, v203
	v_pk_add_f32 v[196:197], v[196:197], 1.0 op_sel_hi:[1,0]
	v_pk_add_f32 v[198:199], v[198:199], 1.0 op_sel_hi:[1,0]
	v_pk_add_f32 v[200:201], v[200:201], 1.0 op_sel_hi:[1,0]
	v_pk_add_f32 v[202:203], v[202:203], 1.0 op_sel_hi:[1,0]
	v_rcp_f32_e32 v196, v196
	v_rcp_f32_e32 v197, v197
	v_rcp_f32_e32 v198, v198
	v_rcp_f32_e32 v199, v199
	v_rcp_f32_e32 v200, v200
	v_rcp_f32_e32 v201, v201
	v_rcp_f32_e32 v202, v202
	v_rcp_f32_e32 v203, v203
	v_pk_mul_f32 v[96:97], v[96:97], v[196:197]
	v_pk_mul_f32 v[98:99], v[98:99], v[198:199]
	v_pk_mul_f32 v[100:101], v[100:101], v[200:201]
	v_pk_mul_f32 v[102:103], v[102:103], v[202:203]
	s_nop 0
	s_nop 0
	s_nop 0
	s_nop 0

; __device__ __forceinline__ float gelu_tanh(float x) { const float u = 1.5957691216f * (x + 0.044715f * x * x * x); return x * __builtin_amdgcn_rcpf(1.f + __expf(-u)); }
; __device__ __forceinline__ void st_bf16x8(bf16_t* p, const f32x4 a, const f32x4 b) { uint4 o; o.x = cvt_pk_bf16(a[0], a[1]); o.y = cvt_pk_bf16(a[2], a[3]); o.z = cvt_pk_bf16(b[0], b[1]); o.w = cvt_pk_bf16(b[2], b[3]); *(uint4*)p = o; }
;     __device__ __forceinline__ void row(const f32x4 (&a)[2][2], int row, int pn, int wc, int fq) const {
;     ...
;             const int head = (pn - 2) * 4 + wc;
;             f32x4 g[2][2]; float ss = 0.f;
; #pragma unroll
;             for (int bj = 0; bj < 2; ++bj)
; #pragma unroll
;                 for (int n = 0; n < 2; ++n)
; #pragma unroll
;                     for (int j = 0; j < 4; ++j) { const float t = gelu_tanh(a[bj][n][j]); g[bj][n][j] = t; ss += t * t; }
;             ss += __shfl_xor(ss, 16); ss += __shfl_xor(ss, 32);
;             const float rs = rsqrtf(ss * (1.f / 64.f) + EPS);
; #pragma unroll
;             for (int bj = 0; bj < 2; ++bj) { const int d = head * 64 + bj * 32 + 8 * fq;
;                 const f32x4 v0 = g[bj][0] * rs * *(const f32x4*)(g_v + d), v1 = g[bj][1] * rs * *(const f32x4*)(g_v + d + 4);
;                 st_bf16x8(pV + (size_t)row * 512 + d, v0, v1);
;                 if (row >= NP && row < NTOK) { float* o = out + O_VS + (size_t)(row - NP) * 512 + d; *(f32x4*)o = v0; *(f32x4*)(o + 4) = v1; } }
.LBB0_255:
	s_andn2_b64 vcc, exec, s[0:1]
	s_cbranch_vccnz .LBB0_260
	v_mov_b32_e32 v190, 0x3d372713
	v_mov_b32_e32 v192, 0xbfcc422a
	v_mov_b32_e32 v194, 0x3fb8aa3b
	v_pk_mul_f32 v[96:97], v[92:93], v[190:191] op_sel_hi:[1,0]
	v_pk_mul_f32 v[100:101], v[94:95], v[190:191] op_sel_hi:[1,0]
	v_pk_mul_f32 v[106:107], v[88:89], v[190:191] op_sel_hi:[1,0]
	v_pk_mul_f32 v[108:109], v[90:91], v[190:191] op_sel_hi:[1,0]
	v_pk_mul_f32 v[110:111], v[84:85], v[190:191] op_sel_hi:[1,0]
	v_pk_mul_f32 v[112:113], v[86:87], v[190:191] op_sel_hi:[1,0]
	v_pk_mul_f32 v[114:115], v[80:81], v[190:191] op_sel_hi:[1,0]
	v_pk_mul_f32 v[116:117], v[82:83], v[190:191] op_sel_hi:[1,0]
	v_pk_mul_f32 v[96:97], v[92:93], v[96:97]
	v_pk_mul_f32 v[100:101], v[94:95], v[100:101]
	v_pk_mul_f32 v[106:107], v[88:89], v[106:107]
	v_pk_mul_f32 v[108:109], v[90:91], v[108:109]
	v_pk_mul_f32 v[110:111], v[84:85], v[110:111]
	v_pk_mul_f32 v[112:113], v[86:87], v[112:113]
	v_pk_mul_f32 v[114:115], v[80:81], v[114:115]
	v_pk_mul_f32 v[116:117], v[82:83], v[116:117]
	v_pk_fma_f32 v[96:97], v[92:93], v[96:97], v[92:93]
	v_pk_fma_f32 v[100:101], v[94:95], v[100:101], v[94:95]
	v_pk_fma_f32 v[106:107], v[88:89], v[106:107], v[88:89]
	v_pk_fma_f32 v[108:109], v[90:91], v[108:109], v[90:91]
	v_pk_fma_f32 v[110:111], v[84:85], v[110:111], v[84:85]
	v_pk_fma_f32 v[112:113], v[86:87], v[112:113], v[86:87]
	v_pk_fma_f32 v[114:115], v[80:81], v[114:115], v[80:81]
	v_pk_fma_f32 v[116:117], v[82:83], v[116:117], v[82:83]
	v_pk_mul_f32 v[96:97], v[96:97], v[192:193] op_sel_hi:[1,0]
	v_pk_mul_f32 v[100:101], v[100:101], v[192:193] op_sel_hi:[1,0]
	v_pk_mul_f32 v[106:107], v[106:107], v[192:193] op_sel_hi:[1,0]
	v_pk_mul_f32 v[108:109], v[108:109], v[192:193] op_sel_hi:[1,0]
	v_pk_mul_f32 v[110:111], v[110:111], v[192:193] op_sel_hi:[1,0]
	v_pk_mul_f32 v[112:113], v[112:113], v[192:193] op_sel_hi:[1,0]
	v_pk_mul_f32 v[114:115], v[114:115], v[192:193] op_sel_hi:[1,0]
	v_pk_mul_f32 v[116:117], v[116:117], v[192:193] op_sel_hi:[1,0]
	v_pk_mul_f32 v[96:97], v[96:97], v[194:195] op_sel_hi:[1,0]
	v_pk_mul_f32 v[100:101], v[100:101], v[194:195] op_sel_hi:[1,0]
	v_pk_mul_f32 v[106:107], v[106:107], v[194:195] op_sel_hi:[1,0]
	v_pk_mul_f32 v[108:109], v[108:109], v[194:195] op_sel_hi:[1,0]
	v_pk_mul_f32 v[110:111], v[110:111], v[194:195] op_sel_hi:[1,0]
	v_pk_mul_f32 v[112:113], v[112:113], v[194:195] op_sel_hi:[1,0]
	v_pk_mul_f32 v[114:115], v[114:115], v[194:195] op_sel_hi:[1,0]
	v_pk_mul_f32 v[116:117], v[116:117], v[194:195] op_sel_hi:[1,0]
	v_exp_f32_e32 v96, v96
	v_exp_f32_e32 v97, v97
	v_exp_f32_e32 v100, v100
	v_exp_f32_e32 v101, v101
	v_exp_f32_e32 v106, v106
	v_exp_f32_e32 v107, v107
	v_exp_f32_e32 v108, v108
	v_exp_f32_e32 v109, v109
	v_exp_f32_e32 v110, v110
	v_exp_f32_e32 v111, v111
	v_exp_f32_e32 v112, v112
	v_exp_f32_e32 v113, v113
	v_exp_f32_e32 v114, v114
	v_exp_f32_e32 v115, v115
	v_exp_f32_e32 v116, v116
	v_exp_f32_e32 v117, v117
	v_pk_add_f32 v[96:97], v[96:97], 1.0 op_sel_hi:[1,0]
	v_pk_add_f32 v[100:101], v[100:101], 1.0 op_sel_hi:[1,0]
	v_pk_add_f32 v[106:107], v[106:107], 1.0 op_sel_hi:[1,0]
	v_pk_add_f32 v[108:109], v[108:109], 1.0 op_sel_hi:[1,0]
	v_pk_add_f32 v[110:111], v[110:111], 1.0 op_sel_hi:[1,0]
	v_pk_add_f32 v[112:113], v[112:113], 1.0 op_sel_hi:[1,0]
	v_pk_add_f32 v[114:115], v[114:115], 1.0 op_sel_hi:[1,0]
	v_pk_add_f32 v[116:117], v[116:117], 1.0 op_sel_hi:[1,0]
	v_rcp_f32_e32 v96, v96
	v_rcp_f32_e32 v97, v97
	v_rcp_f32_e32 v100, v100
	v_rcp_f32_e32 v101, v101
	v_rcp_f32_e32 v106, v106
	v_rcp_f32_e32 v107, v107
	v_rcp_f32_e32 v108, v108
	v_rcp_f32_e32 v109, v109
	v_rcp_f32_e32 v110, v110
	v_rcp_f32_e32 v111, v111
	v_rcp_f32_e32 v112, v112
	v_rcp_f32_e32 v113, v113
	v_rcp_f32_e32 v114, v114
	v_rcp_f32_e32 v115, v115
	v_rcp_f32_e32 v116, v116
	v_rcp_f32_e32 v117, v117
	v_pk_mul_f32 v[96:97], v[92:93], v[96:97]
	v_pk_mul_f32 v[100:101], v[94:95], v[100:101]
	v_pk_mul_f32 v[106:107], v[88:89], v[106:107]
	v_pk_mul_f32 v[108:109], v[90:91], v[108:109]
	v_pk_mul_f32 v[110:111], v[84:85], v[110:111]
	v_pk_mul_f32 v[112:113], v[86:87], v[112:113]
	v_pk_mul_f32 v[114:115], v[80:81], v[114:115]
	v_pk_mul_f32 v[116:117], v[82:83], v[116:117]
	v_pk_mul_f32 v[98:99], v[96:97], v[96:97]
	v_pk_mul_f32 v[102:103], v[100:101], v[100:101]
	v_add_f32_e32 v98, v98, v99
	v_add_f32_e32 v98, v102, v98
	v_pk_mul_f32 v[118:119], v[106:107], v[106:107]
	v_add_f32_e32 v98, v103, v98
	v_add_f32_e32 v98, v118, v98
	v_pk_mul_f32 v[120:121], v[108:109], v[108:109]
	v_add_f32_e32 v98, v119, v98
	v_add_f32_e32 v98, v120, v98
	v_pk_mul_f32 v[122:123], v[110:111], v[110:111]
	v_add_f32_e32 v98, v121, v98
	v_add_f32_e32 v98, v98, v122
	v_pk_mul_f32 v[124:125], v[112:113], v[112:113]
	v_add_f32_e32 v98, v123, v98
	v_add_f32_e32 v98, v124, v98
	v_pk_mul_f32 v[126:127], v[114:115], v[114:115]
	v_add_f32_e32 v98, v125, v98
	v_add_f32_e32 v98, v126, v98
	v_pk_mul_f32 v[128:129], v[116:117], v[116:117]
	v_add_f32_e32 v98, v127, v98
	v_add_f32_e32 v98, v128, v98
	v_add_f32_e32 v98, v129, v98
	ds_bpermute_b32 v99, v229, v98
	v_lshl_add_u64 v[128:129], v[140:141], 2, s[18:19]
	v_ashrrev_i32_e32 v105, 31, v104
	v_lshlrev_b64 v[122:123], 10, v[104:105]
	v_lshlrev_b32_e32 v120, 9, v104
	s_waitcnt lgkmcnt(0)
	v_add_f32_e32 v98, v98, v99
	ds_bpermute_b32 v99, v230, v98
	v_mov_b32_e32 v121, v141
	v_cndmask_b32_e64 v105, 0, 1, s[10:11]
	v_cmp_ne_u32_e64 s[0:1], 1, v105
	s_waitcnt lgkmcnt(0)
	v_add_f32_e32 v98, v98, v99
	v_fmamk_f32 v98, v98, 0x3c800000, v188
	v_cmp_gt_f32_e32 vcc, s13, v98
	v_mul_f32_e32 v99, 0x4b800000, v98
	s_nop 0
	v_cndmask_b32_e32 v98, v98, v99, vcc
	v_rsq_f32_e32 v98, v98
	s_nop 0
	v_mul_f32_e32 v99, 0x45800000, v98
	v_cndmask_b32_e32 v118, v98, v99, vcc
	v_pk_mul_f32 v[124:125], v[96:97], v[118:119] op_sel_hi:[1,0]
	v_pk_mul_f32 v[126:127], v[100:101], v[118:119] op_sel_hi:[1,0]
	global_load_dwordx4 v[96:99], v[128:129], off offset:16
	global_load_dwordx4 v[100:103], v[128:129], off
	v_pk_mul_f32 v[106:107], v[106:107], v[118:119] op_sel_hi:[1,0]
	v_pk_mul_f32 v[108:109], v[108:109], v[118:119] op_sel_hi:[1,0]
	s_andn2_b64 vcc, exec, s[10:11]
	s_waitcnt vmcnt(0)
	v_pk_mul_f32 v[96:97], v[96:97], v[106:107]
	v_lshl_add_u64 v[106:107], s[46:47], 0, v[122:123]
	v_pk_mul_f32 v[102:103], v[102:103], v[126:127]
	v_pk_mul_f32 v[100:101], v[100:101], v[124:125]
	v_pk_mul_f32 v[98:99], v[98:99], v[108:109]
	v_lshl_add_u64 v[106:107], v[140:141], 1, v[106:107]
	v_lshl_add_u64 v[108:109], v[120:121], 2, s[56:57]
	v_cvt_pk_bf16_f32 v122, v100, v101
	v_cvt_pk_bf16_f32 v123, v102, v103
	v_cvt_pk_bf16_f32 v124, v96, v97
	v_cvt_pk_bf16_f32 v125, v98, v99
	global_store_dwordx4 v[106:107], v[122:125], off
	s_cbranch_vccnz .LBB0_258
	v_lshl_add_u64 v[120:121], v[140:141], 2, v[108:109]
	v_lshl_add_u64 v[122:123], v[120:121], 0, s[70:71]
	v_add_co_u32_e32 v120, vcc, 0x2108000, v120
	s_nop 1
	v_addc_co_u32_e32 v121, vcc, 0, v121, vcc
	global_store_dwordx4 v[120:121], v[100:103], off
	global_store_dwordx4 v[122:123], v[96:99], off offset:16

; __device__ __forceinline__ float gelu_tanh(float x) { const float u = 1.5957691216f * (x + 0.044715f * x * x * x); return x * __builtin_amdgcn_rcpf(1.f + __expf(-u)); }
; __device__ __forceinline__ void st_bf16x8(bf16_t* p, const f32x4 a, const f32x4 b) { uint4 o; o.x = cvt_pk_bf16(a[0], a[1]); o.y = cvt_pk_bf16(a[2], a[3]); o.z = cvt_pk_bf16(b[0], b[1]); o.w = cvt_pk_bf16(b[2], b[3]); *(uint4*)p = o; }
;     __device__ __forceinline__ void row(const f32x4 (&a)[2][2], int row, int pn, int wc, int fq) const {
;         if (pn < 2 || pn == 4 || pn == 5) {
;             bf16_t* dst = (pn < 2 ? pU : pBG) + (size_t)row * 512 + (pn & 1) * 256 + wc * 32 + 8 * fq;
; #pragma unroll
;             for (int bj = 0; bj < 2; ++bj) { f32x4 v0 = a[bj][0], v1 = a[bj][1];
;                 if (pn < 2) {
; #pragma unroll
;                     for (int j = 0; j < 4; ++j) { v0[j] = gelu_tanh(v0[j]); v1[j] = gelu_tanh(v1[j]); } }
;                 st_bf16x8(dst + bj * HALF, v0, v1); }
.LBB0_261:
	s_and_b64 vcc, exec, s[4:5]
	s_cbranch_vccnz .LBB0_263
	v_mov_b32_e32 v190, 0x3d372713
	v_mov_b32_e32 v192, 0xbfcc422a
	v_mov_b32_e32 v194, 0x3fb8aa3b
	v_pk_mul_f32 v[196:197], v[88:89], v[190:191] op_sel_hi:[1,0]
	v_pk_mul_f32 v[198:199], v[90:91], v[190:191] op_sel_hi:[1,0]
	v_pk_mul_f32 v[200:201], v[92:93], v[190:191] op_sel_hi:[1,0]
	v_pk_mul_f32 v[202:203], v[94:95], v[190:191] op_sel_hi:[1,0]
	v_pk_mul_f32 v[196:197], v[88:89], v[196:197]
	v_pk_mul_f32 v[198:199], v[90:91], v[198:199]
	v_pk_mul_f32 v[200:201], v[92:93], v[200:201]
	v_pk_mul_f32 v[202:203], v[94:95], v[202:203]
	v_pk_fma_f32 v[196:197], v[88:89], v[196:197], v[88:89]
	v_pk_fma_f32 v[198:199], v[90:91], v[198:199], v[90:91]
	v_pk_fma_f32 v[200:201], v[92:93], v[200:201], v[92:93]
	v_pk_fma_f32 v[202:203], v[94:95], v[202:203], v[94:95]
	v_pk_mul_f32 v[196:197], v[196:197], v[192:193] op_sel_hi:[1,0]
	v_pk_mul_f32 v[198:199], v[198:199], v[192:193] op_sel_hi:[1,0]
	v_pk_mul_f32 v[200:201], v[200:201], v[192:193] op_sel_hi:[1,0]
	v_pk_mul_f32 v[202:203], v[202:203], v[192:193] op_sel_hi:[1,0]
	v_pk_mul_f32 v[196:197], v[196:197], v[194:195] op_sel_hi:[1,0]
	v_pk_mul_f32 v[198:199], v[198:199], v[194:195] op_sel_hi:[1,0]
	v_pk_mul_f32 v[200:201], v[200:201], v[194:195] op_sel_hi:[1,0]
	v_pk_mul_f32 v[202:203], v[202:203], v[194:195] op_sel_hi:[1,0]
	v_exp_f32_e32 v196, v196
	v_exp_f32_e32 v197, v197
	v_exp_f32_e32 v198, v198
	v_exp_f32_e32 v199, v199
	v_exp_f32_e32 v200, v200
	v_exp_f32_e32 v201, v201
	v_exp_f32_e32 v202, v202
	v_exp_f32_e32 v203, v203
	v_pk_add_f32 v[196:197], v[196:197], 1.0 op_sel_hi:[1,0]
	v_pk_add_f32 v[198:199], v[198:199], 1.0 op_sel_hi:[1,0]
	v_pk_add_f32 v[200:201], v[200:201], 1.0 op_sel_hi:[1,0]
	v_pk_add_f32 v[202:203], v[202:203], 1.0 op_sel_hi:[1,0]
	v_rcp_f32_e32 v196, v196
	v_rcp_f32_e32 v197, v197
	v_rcp_f32_e32 v198, v198
	v_rcp_f32_e32 v199, v199
	v_rcp_f32_e32 v200, v200
	v_rcp_f32_e32 v201, v201
	v_rcp_f32_e32 v202, v202
	v_rcp_f32_e32 v203, v203
	v_pk_mul_f32 v[88:89], v[88:89], v[196:197]
	v_pk_mul_f32 v[90:91], v[90:91], v[198:199]
	v_pk_mul_f32 v[92:93], v[92:93], v[200:201]
	v_pk_mul_f32 v[94:95], v[94:95], v[202:203]
	s_nop 0
	s_nop 0
	s_nop 0
	s_nop 0
.LBB0_263:
	s_and_b64 s[0:1], s[80:81], exec
	v_ashrrev_i32_e32 v105, 31, v104
	s_cselect_b32 s1, s31, s49
	s_cselect_b32 s0, s30, s48
	v_lshlrev_b64 v[96:97], 10, v[104:105]
	v_lshl_add_u64 v[96:97], s[0:1], 0, v[96:97]
	s_lshl_b32 s64, s61, 1
	v_lshl_add_u64 v[96:97], v[96:97], 0, s[64:65]
	s_lshl_b32 s64, s91, 1
	v_lshl_add_u64 v[96:97], v[96:97], 0, s[64:65]
	v_lshlrev_b32_e32 v98, 1, v142
	v_mov_b32_e32 v99, v141
	v_lshl_add_u64 v[96:97], v[96:97], 0, v[98:99]
	s_and_b64 vcc, exec, s[4:5]
	v_cvt_pk_bf16_f32 v92, v92, v93
	v_cvt_pk_bf16_f32 v93, v94, v95
	v_cvt_pk_bf16_f32 v94, v88, v89
	v_cvt_pk_bf16_f32 v95, v90, v91
	global_store_dwordx4 v[96:97], v[92:95], off
	s_cbranch_vccnz .LBB0_265
	v_mov_b32_e32 v190, 0x3d372713
	v_mov_b32_e32 v192, 0xbfcc422a
	v_mov_b32_e32 v194, 0x3fb8aa3b
	v_pk_mul_f32 v[196:197], v[80:81], v[190:191] op_sel_hi:[1,0]
	v_pk_mul_f32 v[198:199], v[82:83], v[190:191] op_sel_hi:[1,0]
	v_pk_mul_f32 v[200:201], v[84:85], v[190:191] op_sel_hi:[1,0]
	v_pk_mul_f32 v[202:203], v[86:87], v[190:191] op_sel_hi:[1,0]
	v_pk_mul_f32 v[196:197], v[80:81], v[196:197]
	v_pk_mul_f32 v[198:199], v[82:83], v[198:199]
	v_pk_mul_f32 v[200:201], v[84:85], v[200:201]
	v_pk_mul_f32 v[202:203], v[86:87], v[202:203]
	v_pk_fma_f32 v[196:197], v[80:81], v[196:197], v[80:81]
	v_pk_fma_f32 v[198:199], v[82:83], v[198:199], v[82:83]
	v_pk_fma_f32 v[200:201], v[84:85], v[200:201], v[84:85]
	v_pk_fma_f32 v[202:203], v[86:87], v[202:203], v[86:87]
	v_pk_mul_f32 v[196:197], v[196:197], v[192:193] op_sel_hi:[1,0]
	v_pk_mul_f32 v[198:199], v[198:199], v[192:193] op_sel_hi:[1,0]
	v_pk_mul_f32 v[200:201], v[200:201], v[192:193] op_sel_hi:[1,0]
	v_pk_mul_f32 v[202:203], v[202:203], v[192:193] op_sel_hi:[1,0]
	v_pk_mul_f32 v[196:197], v[196:197], v[194:195] op_sel_hi:[1,0]
	v_pk_mul_f32 v[198:199], v[198:199], v[194:195] op_sel_hi:[1,0]
	v_pk_mul_f32 v[200:201], v[200:201], v[194:195] op_sel_hi:[1,0]
	v_pk_mul_f32 v[202:203], v[202:203], v[194:195] op_sel_hi:[1,0]
	v_exp_f32_e32 v196, v196
	v_exp_f32_e32 v197, v197
	v_exp_f32_e32 v198, v198
	v_exp_f32_e32 v199, v199
	v_exp_f32_e32 v200, v200
	v_exp_f32_e32 v201, v201
	v_exp_f32_e32 v202, v202
	v_exp_f32_e32 v203, v203
	v_pk_add_f32 v[196:197], v[196:197], 1.0 op_sel_hi:[1,0]
	v_pk_add_f32 v[198:199], v[198:199], 1.0 op_sel_hi:[1,0]
	v_pk_add_f32 v[200:201], v[200:201], 1.0 op_sel_hi:[1,0]
	v_pk_add_f32 v[202:203], v[202:203], 1.0 op_sel_hi:[1,0]
	v_rcp_f32_e32 v196, v196
	v_rcp_f32_e32 v197, v197
	v_rcp_f32_e32 v198, v198
	v_rcp_f32_e32 v199, v199
	v_rcp_f32_e32 v200, v200
	v_rcp_f32_e32 v201, v201
	v_rcp_f32_e32 v202, v202
	v_rcp_f32_e32 v203, v203
	v_pk_mul_f32 v[80:81], v[80:81], v[196:197]
	v_pk_mul_f32 v[82:83], v[82:83], v[198:199]
	v_pk_mul_f32 v[84:85], v[84:85], v[200:201]
	v_pk_mul_f32 v[86:87], v[86:87], v[202:203]
	s_nop 0
	s_nop 0
	s_nop 0
	s_nop 0

; __device__ __forceinline__ float gelu_tanh(float x) { const float u = 1.5957691216f * (x + 0.044715f * x * x * x); return x * __builtin_amdgcn_rcpf(1.f + __expf(-u)); }
; __device__ __forceinline__ void st_bf16x8(bf16_t* p, const f32x4 a, const f32x4 b) { uint4 o; o.x = cvt_pk_bf16(a[0], a[1]); o.y = cvt_pk_bf16(a[2], a[3]); o.z = cvt_pk_bf16(b[0], b[1]); o.w = cvt_pk_bf16(b[2], b[3]); *(uint4*)p = o; }
;     __device__ __forceinline__ void row(const f32x4 (&a)[2][2], int row, int pn, int wc, int fq) const {
;     ...
;             const int head = (pn - 2) * 4 + wc;
;             f32x4 g[2][2]; float ss = 0.f;
; #pragma unroll
;             for (int bj = 0; bj < 2; ++bj)
; #pragma unroll
;                 for (int n = 0; n < 2; ++n)
; #pragma unroll
;                     for (int j = 0; j < 4; ++j) { const float t = gelu_tanh(a[bj][n][j]); g[bj][n][j] = t; ss += t * t; }
;             ss += __shfl_xor(ss, 16); ss += __shfl_xor(ss, 32);
;             const float rs = rsqrtf(ss * (1.f / 64.f) + EPS);
; #pragma unroll
;             for (int bj = 0; bj < 2; ++bj) { const int d = head * 64 + bj * 32 + 8 * fq;
;                 const f32x4 v0 = g[bj][0] * rs * *(const f32x4*)(g_v + d), v1 = g[bj][1] * rs * *(const f32x4*)(g_v + d + 4);
;                 st_bf16x8(pV + (size_t)row * 512 + d, v0, v1);
;                 if (row >= NP && row < NTOK) { float* o = out + O_VS + (size_t)(row - NP) * 512 + d; *(f32x4*)o = v0; *(f32x4*)(o + 4) = v1; } }
.LBB0_272:
	s_and_b64 vcc, exec, s[0:1]
	s_cbranch_vccz .LBB0_277
	v_mov_b32_e32 v190, 0x3d372713
	v_mov_b32_e32 v192, 0xbfcc422a
	v_mov_b32_e32 v194, 0x3fb8aa3b
	v_pk_mul_f32 v[80:81], v[76:77], v[190:191] op_sel_hi:[1,0]
	v_pk_mul_f32 v[84:85], v[78:79], v[190:191] op_sel_hi:[1,0]
	v_pk_mul_f32 v[90:91], v[72:73], v[190:191] op_sel_hi:[1,0]
	v_pk_mul_f32 v[92:93], v[74:75], v[190:191] op_sel_hi:[1,0]
	v_pk_mul_f32 v[94:95], v[68:69], v[190:191] op_sel_hi:[1,0]
	v_pk_mul_f32 v[96:97], v[70:71], v[190:191] op_sel_hi:[1,0]
	v_pk_mul_f32 v[98:99], v[64:65], v[190:191] op_sel_hi:[1,0]
	v_pk_mul_f32 v[100:101], v[66:67], v[190:191] op_sel_hi:[1,0]
	v_pk_mul_f32 v[80:81], v[76:77], v[80:81]
	v_pk_mul_f32 v[84:85], v[78:79], v[84:85]
	v_pk_mul_f32 v[90:91], v[72:73], v[90:91]
	v_pk_mul_f32 v[92:93], v[74:75], v[92:93]
	v_pk_mul_f32 v[94:95], v[68:69], v[94:95]
	v_pk_mul_f32 v[96:97], v[70:71], v[96:97]
	v_pk_mul_f32 v[98:99], v[64:65], v[98:99]
	v_pk_mul_f32 v[100:101], v[66:67], v[100:101]
	v_pk_fma_f32 v[80:81], v[76:77], v[80:81], v[76:77]
	v_pk_fma_f32 v[84:85], v[78:79], v[84:85], v[78:79]
	v_pk_fma_f32 v[90:91], v[72:73], v[90:91], v[72:73]
	v_pk_fma_f32 v[92:93], v[74:75], v[92:93], v[74:75]
	v_pk_fma_f32 v[94:95], v[68:69], v[94:95], v[68:69]
	v_pk_fma_f32 v[96:97], v[70:71], v[96:97], v[70:71]
	v_pk_fma_f32 v[98:99], v[64:65], v[98:99], v[64:65]
	v_pk_fma_f32 v[100:101], v[66:67], v[100:101], v[66:67]
	v_pk_mul_f32 v[80:81], v[80:81], v[192:193] op_sel_hi:[1,0]
	v_pk_mul_f32 v[84:85], v[84:85], v[192:193] op_sel_hi:[1,0]
	v_pk_mul_f32 v[90:91], v[90:91], v[192:193] op_sel_hi:[1,0]
	v_pk_mul_f32 v[92:93], v[92:93], v[192:193] op_sel_hi:[1,0]
	v_pk_mul_f32 v[94:95], v[94:95], v[192:193] op_sel_hi:[1,0]
	v_pk_mul_f32 v[96:97], v[96:97], v[192:193] op_sel_hi:[1,0]
	v_pk_mul_f32 v[98:99], v[98:99], v[192:193] op_sel_hi:[1,0]
	v_pk_mul_f32 v[100:101], v[100:101], v[192:193] op_sel_hi:[1,0]
	v_pk_mul_f32 v[80:81], v[80:81], v[194:195] op_sel_hi:[1,0]
	v_pk_mul_f32 v[84:85], v[84:85], v[194:195] op_sel_hi:[1,0]
	v_pk_mul_f32 v[90:91], v[90:91], v[194:195] op_sel_hi:[1,0]
	v_pk_mul_f32 v[92:93], v[92:93], v[194:195] op_sel_hi:[1,0]
	v_pk_mul_f32 v[94:95], v[94:95], v[194:195] op_sel_hi:[1,0]
	v_pk_mul_f32 v[96:97], v[96:97], v[194:195] op_sel_hi:[1,0]
	v_pk_mul_f32 v[98:99], v[98:99], v[194:195] op_sel_hi:[1,0]
	v_pk_mul_f32 v[100:101], v[100:101], v[194:195] op_sel_hi:[1,0]
	v_exp_f32_e32 v80, v80
	v_exp_f32_e32 v81, v81
	v_exp_f32_e32 v84, v84
	v_exp_f32_e32 v85, v85
	v_exp_f32_e32 v90, v90
	v_exp_f32_e32 v91, v91
	v_exp_f32_e32 v92, v92
	v_exp_f32_e32 v93, v93
	v_exp_f32_e32 v94, v94
	v_exp_f32_e32 v95, v95
	v_exp_f32_e32 v96, v96
	v_exp_f32_e32 v97, v97
	v_exp_f32_e32 v98, v98
	v_exp_f32_e32 v99, v99
	v_exp_f32_e32 v100, v100
	v_exp_f32_e32 v101, v101
	v_pk_add_f32 v[80:81], v[80:81], 1.0 op_sel_hi:[1,0]
	v_pk_add_f32 v[84:85], v[84:85], 1.0 op_sel_hi:[1,0]
	v_pk_add_f32 v[90:91], v[90:91], 1.0 op_sel_hi:[1,0]
	v_pk_add_f32 v[92:93], v[92:93], 1.0 op_sel_hi:[1,0]
	v_pk_add_f32 v[94:95], v[94:95], 1.0 op_sel_hi:[1,0]
	v_pk_add_f32 v[96:97], v[96:97], 1.0 op_sel_hi:[1,0]
	v_pk_add_f32 v[98:99], v[98:99], 1.0 op_sel_hi:[1,0]
	v_pk_add_f32 v[100:101], v[100:101], 1.0 op_sel_hi:[1,0]
	v_rcp_f32_e32 v80, v80
	v_rcp_f32_e32 v81, v81
	v_rcp_f32_e32 v84, v84
	v_rcp_f32_e32 v85, v85
	v_rcp_f32_e32 v90, v90
	v_rcp_f32_e32 v91, v91
	v_rcp_f32_e32 v92, v92
	v_rcp_f32_e32 v93, v93
	v_rcp_f32_e32 v94, v94
	v_rcp_f32_e32 v95, v95
	v_rcp_f32_e32 v96, v96
	v_rcp_f32_e32 v97, v97
	v_rcp_f32_e32 v98, v98
	v_rcp_f32_e32 v99, v99
	v_rcp_f32_e32 v100, v100
	v_rcp_f32_e32 v101, v101
	v_pk_mul_f32 v[80:81], v[76:77], v[80:81]
	v_pk_mul_f32 v[84:85], v[78:79], v[84:85]
	v_pk_mul_f32 v[90:91], v[72:73], v[90:91]
	v_pk_mul_f32 v[92:93], v[74:75], v[92:93]
	v_pk_mul_f32 v[94:95], v[68:69], v[94:95]
	v_pk_mul_f32 v[96:97], v[70:71], v[96:97]
	v_pk_mul_f32 v[98:99], v[64:65], v[98:99]
	v_pk_mul_f32 v[100:101], v[66:67], v[100:101]
	v_pk_mul_f32 v[82:83], v[80:81], v[80:81]
	v_pk_mul_f32 v[86:87], v[84:85], v[84:85]
	v_add_f32_e32 v82, v82, v83
	v_add_f32_e32 v82, v86, v82
	v_pk_mul_f32 v[102:103], v[90:91], v[90:91]
	v_add_f32_e32 v82, v87, v82
	v_add_f32_e32 v82, v102, v82
	v_pk_mul_f32 v[104:105], v[92:93], v[92:93]
	v_add_f32_e32 v82, v103, v82
	v_add_f32_e32 v82, v104, v82
	v_pk_mul_f32 v[106:107], v[94:95], v[94:95]
	v_add_f32_e32 v82, v105, v82
	v_add_f32_e32 v82, v82, v106
	v_pk_mul_f32 v[108:109], v[96:97], v[96:97]
	v_add_f32_e32 v82, v107, v82
	v_add_f32_e32 v82, v108, v82
	v_pk_mul_f32 v[110:111], v[98:99], v[98:99]
	v_add_f32_e32 v82, v109, v82
	v_add_f32_e32 v82, v110, v82
	v_pk_mul_f32 v[112:113], v[100:101], v[100:101]
	v_add_f32_e32 v82, v111, v82
	v_add_f32_e32 v82, v112, v82
	v_add_f32_e32 v82, v113, v82
	ds_bpermute_b32 v83, v229, v82
	v_lshl_add_u64 v[112:113], v[140:141], 2, s[18:19]
	v_ashrrev_i32_e32 v89, 31, v88
	v_lshlrev_b64 v[106:107], 10, v[88:89]
	v_lshlrev_b32_e32 v104, 9, v88
	s_waitcnt lgkmcnt(0)
	v_add_f32_e32 v82, v82, v83
	ds_bpermute_b32 v83, v230, v82
	v_mov_b32_e32 v105, v141
	v_cndmask_b32_e64 v89, 0, 1, s[10:11]
	v_cmp_ne_u32_e64 s[0:1], 1, v89
	s_waitcnt lgkmcnt(0)
	v_add_f32_e32 v82, v82, v83
	v_fmamk_f32 v82, v82, 0x3c800000, v188
	v_cmp_gt_f32_e32 vcc, s13, v82
	v_mul_f32_e32 v83, 0x4b800000, v82
	s_nop 0
	v_cndmask_b32_e32 v82, v82, v83, vcc
	v_rsq_f32_e32 v82, v82
	s_nop 0
	v_mul_f32_e32 v83, 0x45800000, v82
	v_cndmask_b32_e32 v102, v82, v83, vcc
	v_pk_mul_f32 v[108:109], v[80:81], v[102:103] op_sel_hi:[1,0]
	v_pk_mul_f32 v[110:111], v[84:85], v[102:103] op_sel_hi:[1,0]
	global_load_dwordx4 v[80:83], v[112:113], off offset:16
	global_load_dwordx4 v[84:87], v[112:113], off
	v_pk_mul_f32 v[90:91], v[90:91], v[102:103] op_sel_hi:[1,0]
	v_pk_mul_f32 v[92:93], v[92:93], v[102:103] op_sel_hi:[1,0]
	s_andn2_b64 vcc, exec, s[10:11]
	s_waitcnt vmcnt(0)
	v_pk_mul_f32 v[80:81], v[80:81], v[90:91]
	v_lshl_add_u64 v[90:91], s[46:47], 0, v[106:107]
	v_pk_mul_f32 v[86:87], v[86:87], v[110:111]
	v_pk_mul_f32 v[84:85], v[84:85], v[108:109]
	v_pk_mul_f32 v[82:83], v[82:83], v[92:93]
	v_lshl_add_u64 v[90:91], v[140:141], 1, v[90:91]
	v_lshl_add_u64 v[92:93], v[104:105], 2, s[56:57]
	v_cvt_pk_bf16_f32 v106, v84, v85
	v_cvt_pk_bf16_f32 v107, v86, v87
	v_cvt_pk_bf16_f32 v108, v80, v81
	v_cvt_pk_bf16_f32 v109, v82, v83
	global_store_dwordx4 v[90:91], v[106:109], off
	s_cbranch_vccnz .LBB0_275
	v_lshl_add_u64 v[104:105], v[140:141], 2, v[92:93]
	v_lshl_add_u64 v[106:107], v[104:105], 0, s[70:71]
	v_add_co_u32_e32 v104, vcc, 0x2108000, v104
	s_nop 1
	v_addc_co_u32_e32 v105, vcc, 0, v105, vcc
	global_store_dwordx4 v[104:105], v[84:87], off
	global_store_dwordx4 v[106:107], v[80:83], off offset:16

; __device__ __forceinline__ float gelu_tanh(float x) { const float u = 1.5957691216f * (x + 0.044715f * x * x * x); return x * __builtin_amdgcn_rcpf(1.f + __expf(-u)); }
; __device__ __forceinline__ void st_bf16x8(bf16_t* p, const f32x4 a, const f32x4 b) { uint4 o; o.x = cvt_pk_bf16(a[0], a[1]); o.y = cvt_pk_bf16(a[2], a[3]); o.z = cvt_pk_bf16(b[0], b[1]); o.w = cvt_pk_bf16(b[2], b[3]); *(uint4*)p = o; }
;     __device__ __forceinline__ void row(const f32x4 (&a)[2][2], int row, int pn, int wc, int fq) const {
;         if (pn < 2 || pn == 4 || pn == 5) {
;             bf16_t* dst = (pn < 2 ? pU : pBG) + (size_t)row * 512 + (pn & 1) * 256 + wc * 32 + 8 * fq;
; #pragma unroll
;             for (int bj = 0; bj < 2; ++bj) { f32x4 v0 = a[bj][0], v1 = a[bj][1];
;                 if (pn < 2) {
; #pragma unroll
;                     for (int j = 0; j < 4; ++j) { v0[j] = gelu_tanh(v0[j]); v1[j] = gelu_tanh(v1[j]); } }
;                 st_bf16x8(dst + bj * HALF, v0, v1); }
.LBB0_278:
	s_and_b64 vcc, exec, s[4:5]
	s_cbranch_vccnz .LBB0_280
	v_mov_b32_e32 v190, 0x3d372713
	v_mov_b32_e32 v192, 0xbfcc422a
	v_mov_b32_e32 v194, 0x3fb8aa3b
	v_pk_mul_f32 v[196:197], v[72:73], v[190:191] op_sel_hi:[1,0]
	v_pk_mul_f32 v[198:199], v[74:75], v[190:191] op_sel_hi:[1,0]
	v_pk_mul_f32 v[200:201], v[76:77], v[190:191] op_sel_hi:[1,0]
	v_pk_mul_f32 v[202:203], v[78:79], v[190:191] op_sel_hi:[1,0]
	v_pk_mul_f32 v[196:197], v[72:73], v[196:197]
	v_pk_mul_f32 v[198:199], v[74:75], v[198:199]
	v_pk_mul_f32 v[200:201], v[76:77], v[200:201]
	v_pk_mul_f32 v[202:203], v[78:79], v[202:203]
	v_pk_fma_f32 v[196:197], v[72:73], v[196:197], v[72:73]
	v_pk_fma_f32 v[198:199], v[74:75], v[198:199], v[74:75]
	v_pk_fma_f32 v[200:201], v[76:77], v[200:201], v[76:77]
	v_pk_fma_f32 v[202:203], v[78:79], v[202:203], v[78:79]
	v_pk_mul_f32 v[196:197], v[196:197], v[192:193] op_sel_hi:[1,0]
	v_pk_mul_f32 v[198:199], v[198:199], v[192:193] op_sel_hi:[1,0]
	v_pk_mul_f32 v[200:201], v[200:201], v[192:193] op_sel_hi:[1,0]
	v_pk_mul_f32 v[202:203], v[202:203], v[192:193] op_sel_hi:[1,0]
	v_pk_mul_f32 v[196:197], v[196:197], v[194:195] op_sel_hi:[1,0]
	v_pk_mul_f32 v[198:199], v[198:199], v[194:195] op_sel_hi:[1,0]
	v_pk_mul_f32 v[200:201], v[200:201], v[194:195] op_sel_hi:[1,0]
	v_pk_mul_f32 v[202:203], v[202:203], v[194:195] op_sel_hi:[1,0]
	v_exp_f32_e32 v196, v196
	v_exp_f32_e32 v197, v197
	v_exp_f32_e32 v198, v198
	v_exp_f32_e32 v199, v199
	v_exp_f32_e32 v200, v200
	v_exp_f32_e32 v201, v201
	v_exp_f32_e32 v202, v202
	v_exp_f32_e32 v203, v203
	v_pk_add_f32 v[196:197], v[196:197], 1.0 op_sel_hi:[1,0]
	v_pk_add_f32 v[198:199], v[198:199], 1.0 op_sel_hi:[1,0]
	v_pk_add_f32 v[200:201], v[200:201], 1.0 op_sel_hi:[1,0]
	v_pk_add_f32 v[202:203], v[202:203], 1.0 op_sel_hi:[1,0]
	v_rcp_f32_e32 v196, v196
	v_rcp_f32_e32 v197, v197
	v_rcp_f32_e32 v198, v198
	v_rcp_f32_e32 v199, v199
	v_rcp_f32_e32 v200, v200
	v_rcp_f32_e32 v201, v201
	v_rcp_f32_e32 v202, v202
	v_rcp_f32_e32 v203, v203
	v_pk_mul_f32 v[72:73], v[72:73], v[196:197]
	v_pk_mul_f32 v[74:75], v[74:75], v[198:199]
	v_pk_mul_f32 v[76:77], v[76:77], v[200:201]
	v_pk_mul_f32 v[78:79], v[78:79], v[202:203]
	s_nop 0
	s_nop 0
	s_nop 0
	s_nop 0
.LBB0_280:
	s_and_b64 s[0:1], s[80:81], exec
	v_ashrrev_i32_e32 v89, 31, v88
	s_cselect_b32 s1, s31, s49
	s_cselect_b32 s0, s30, s48
	v_lshlrev_b64 v[80:81], 10, v[88:89]
	v_lshl_add_u64 v[80:81], s[0:1], 0, v[80:81]
	s_lshl_b32 s64, s61, 1
	v_lshl_add_u64 v[80:81], v[80:81], 0, s[64:65]
	s_lshl_b32 s64, s91, 1
	v_lshl_add_u64 v[80:81], v[80:81], 0, s[64:65]
	v_lshlrev_b32_e32 v82, 1, v142
	v_mov_b32_e32 v83, v141
	v_lshl_add_u64 v[80:81], v[80:81], 0, v[82:83]
	s_and_b64 vcc, exec, s[4:5]
	v_cvt_pk_bf16_f32 v76, v76, v77
	v_cvt_pk_bf16_f32 v77, v78, v79
	v_cvt_pk_bf16_f32 v78, v72, v73
	v_cvt_pk_bf16_f32 v79, v74, v75
	global_store_dwordx4 v[80:81], v[76:79], off
	s_cbranch_vccnz .LBB0_282
	v_mov_b32_e32 v190, 0x3d372713
	v_mov_b32_e32 v192, 0xbfcc422a
	v_mov_b32_e32 v194, 0x3fb8aa3b
	v_pk_mul_f32 v[196:197], v[64:65], v[190:191] op_sel_hi:[1,0]
	v_pk_mul_f32 v[198:199], v[66:67], v[190:191] op_sel_hi:[1,0]
	v_pk_mul_f32 v[200:201], v[68:69], v[190:191] op_sel_hi:[1,0]
	v_pk_mul_f32 v[202:203], v[70:71], v[190:191] op_sel_hi:[1,0]
	v_pk_mul_f32 v[196:197], v[64:65], v[196:197]
	v_pk_mul_f32 v[198:199], v[66:67], v[198:199]
	v_pk_mul_f32 v[200:201], v[68:69], v[200:201]
	v_pk_mul_f32 v[202:203], v[70:71], v[202:203]
	v_pk_fma_f32 v[196:197], v[64:65], v[196:197], v[64:65]
	v_pk_fma_f32 v[198:199], v[66:67], v[198:199], v[66:67]
	v_pk_fma_f32 v[200:201], v[68:69], v[200:201], v[68:69]
	v_pk_fma_f32 v[202:203], v[70:71], v[202:203], v[70:71]
	v_pk_mul_f32 v[196:197], v[196:197], v[192:193] op_sel_hi:[1,0]
	v_pk_mul_f32 v[198:199], v[198:199], v[192:193] op_sel_hi:[1,0]
	v_pk_mul_f32 v[200:201], v[200:201], v[192:193] op_sel_hi:[1,0]
	v_pk_mul_f32 v[202:203], v[202:203], v[192:193] op_sel_hi:[1,0]
	v_pk_mul_f32 v[196:197], v[196:197], v[194:195] op_sel_hi:[1,0]
	v_pk_mul_f32 v[198:199], v[198:199], v[194:195] op_sel_hi:[1,0]
	v_pk_mul_f32 v[200:201], v[200:201], v[194:195] op_sel_hi:[1,0]
	v_pk_mul_f32 v[202:203], v[202:203], v[194:195] op_sel_hi:[1,0]
	v_exp_f32_e32 v196, v196
	v_exp_f32_e32 v197, v197
	v_exp_f32_e32 v198, v198
	v_exp_f32_e32 v199, v199
	v_exp_f32_e32 v200, v200
	v_exp_f32_e32 v201, v201
	v_exp_f32_e32 v202, v202
	v_exp_f32_e32 v203, v203
	v_pk_add_f32 v[196:197], v[196:197], 1.0 op_sel_hi:[1,0]
	v_pk_add_f32 v[198:199], v[198:199], 1.0 op_sel_hi:[1,0]
	v_pk_add_f32 v[200:201], v[200:201], 1.0 op_sel_hi:[1,0]
	v_pk_add_f32 v[202:203], v[202:203], 1.0 op_sel_hi:[1,0]
	v_rcp_f32_e32 v196, v196
	v_rcp_f32_e32 v197, v197
	v_rcp_f32_e32 v198, v198
	v_rcp_f32_e32 v199, v199
	v_rcp_f32_e32 v200, v200
	v_rcp_f32_e32 v201, v201
	v_rcp_f32_e32 v202, v202
	v_rcp_f32_e32 v203, v203
	v_pk_mul_f32 v[64:65], v[64:65], v[196:197]
	v_pk_mul_f32 v[66:67], v[66:67], v[198:199]
	v_pk_mul_f32 v[68:69], v[68:69], v[200:201]
	v_pk_mul_f32 v[70:71], v[70:71], v[202:203]
	s_nop 0
	s_nop 0
	s_nop 0
	s_nop 0

; __device__ __forceinline__ float gelu_tanh(float x) { const float u = 1.5957691216f * (x + 0.044715f * x * x * x); return x * __builtin_amdgcn_rcpf(1.f + __expf(-u)); }
; __device__ __forceinline__ void st_bf16x8(bf16_t* p, const f32x4 a, const f32x4 b) { uint4 o; o.x = cvt_pk_bf16(a[0], a[1]); o.y = cvt_pk_bf16(a[2], a[3]); o.z = cvt_pk_bf16(b[0], b[1]); o.w = cvt_pk_bf16(b[2], b[3]); *(uint4*)p = o; }
;     __device__ __forceinline__ void row(const f32x4 (&a)[2][2], int row, int pn, int wc, int fq) const {
;     ...
;             const int head = (pn - 2) * 4 + wc;
;             f32x4 g[2][2]; float ss = 0.f;
; #pragma unroll
;             for (int bj = 0; bj < 2; ++bj)
; #pragma unroll
;                 for (int n = 0; n < 2; ++n)
; #pragma unroll
;                     for (int j = 0; j < 4; ++j) { const float t = gelu_tanh(a[bj][n][j]); g[bj][n][j] = t; ss += t * t; }
;             ss += __shfl_xor(ss, 16); ss += __shfl_xor(ss, 32);
;             const float rs = rsqrtf(ss * (1.f / 64.f) + EPS);
; #pragma unroll
;             for (int bj = 0; bj < 2; ++bj) { const int d = head * 64 + bj * 32 + 8 * fq;
;                 const f32x4 v0 = g[bj][0] * rs * *(const f32x4*)(g_v + d), v1 = g[bj][1] * rs * *(const f32x4*)(g_v + d + 4);
;                 st_bf16x8(pV + (size_t)row * 512 + d, v0, v1);
;                 if (row >= NP && row < NTOK) { float* o = out + O_VS + (size_t)(row - NP) * 512 + d; *(f32x4*)o = v0; *(f32x4*)(o + 4) = v1; } }
.LBB0_295:
	s_andn2_b64 vcc, exec, s[0:1]
	s_cbranch_vccnz .LBB0_301
	v_mov_b32_e32 v190, 0x3d372713
	v_mov_b32_e32 v192, 0xbfcc422a
	v_mov_b32_e32 v194, 0x3fb8aa3b
	v_pk_mul_f32 v[64:65], v[60:61], v[190:191] op_sel_hi:[1,0]
	v_pk_mul_f32 v[68:69], v[62:63], v[190:191] op_sel_hi:[1,0]
	v_pk_mul_f32 v[74:75], v[56:57], v[190:191] op_sel_hi:[1,0]
	v_pk_mul_f32 v[76:77], v[58:59], v[190:191] op_sel_hi:[1,0]
	v_pk_mul_f32 v[78:79], v[52:53], v[190:191] op_sel_hi:[1,0]
	v_pk_mul_f32 v[80:81], v[54:55], v[190:191] op_sel_hi:[1,0]
	v_pk_mul_f32 v[82:83], v[48:49], v[190:191] op_sel_hi:[1,0]
	v_pk_mul_f32 v[84:85], v[50:51], v[190:191] op_sel_hi:[1,0]
	v_pk_mul_f32 v[64:65], v[60:61], v[64:65]
	v_pk_mul_f32 v[68:69], v[62:63], v[68:69]
	v_pk_mul_f32 v[74:75], v[56:57], v[74:75]
	v_pk_mul_f32 v[76:77], v[58:59], v[76:77]
	v_pk_mul_f32 v[78:79], v[52:53], v[78:79]
	v_pk_mul_f32 v[80:81], v[54:55], v[80:81]
	v_pk_mul_f32 v[82:83], v[48:49], v[82:83]
	v_pk_mul_f32 v[84:85], v[50:51], v[84:85]
	v_pk_fma_f32 v[64:65], v[60:61], v[64:65], v[60:61]
	v_pk_fma_f32 v[68:69], v[62:63], v[68:69], v[62:63]
	v_pk_fma_f32 v[74:75], v[56:57], v[74:75], v[56:57]
	v_pk_fma_f32 v[76:77], v[58:59], v[76:77], v[58:59]
	v_pk_fma_f32 v[78:79], v[52:53], v[78:79], v[52:53]
	v_pk_fma_f32 v[80:81], v[54:55], v[80:81], v[54:55]
	v_pk_fma_f32 v[82:83], v[48:49], v[82:83], v[48:49]
	v_pk_fma_f32 v[84:85], v[50:51], v[84:85], v[50:51]
	v_pk_mul_f32 v[64:65], v[64:65], v[192:193] op_sel_hi:[1,0]
	v_pk_mul_f32 v[68:69], v[68:69], v[192:193] op_sel_hi:[1,0]
	v_pk_mul_f32 v[74:75], v[74:75], v[192:193] op_sel_hi:[1,0]
	v_pk_mul_f32 v[76:77], v[76:77], v[192:193] op_sel_hi:[1,0]
	v_pk_mul_f32 v[78:79], v[78:79], v[192:193] op_sel_hi:[1,0]
	v_pk_mul_f32 v[80:81], v[80:81], v[192:193] op_sel_hi:[1,0]
	v_pk_mul_f32 v[82:83], v[82:83], v[192:193] op_sel_hi:[1,0]
	v_pk_mul_f32 v[84:85], v[84:85], v[192:193] op_sel_hi:[1,0]
	v_pk_mul_f32 v[64:65], v[64:65], v[194:195] op_sel_hi:[1,0]
	v_pk_mul_f32 v[68:69], v[68:69], v[194:195] op_sel_hi:[1,0]
	v_pk_mul_f32 v[74:75], v[74:75], v[194:195] op_sel_hi:[1,0]
	v_pk_mul_f32 v[76:77], v[76:77], v[194:195] op_sel_hi:[1,0]
	v_pk_mul_f32 v[78:79], v[78:79], v[194:195] op_sel_hi:[1,0]
	v_pk_mul_f32 v[80:81], v[80:81], v[194:195] op_sel_hi:[1,0]
	v_pk_mul_f32 v[82:83], v[82:83], v[194:195] op_sel_hi:[1,0]
	v_pk_mul_f32 v[84:85], v[84:85], v[194:195] op_sel_hi:[1,0]
	v_exp_f32_e32 v64, v64
	v_exp_f32_e32 v65, v65
	v_exp_f32_e32 v68, v68
	v_exp_f32_e32 v69, v69
	v_exp_f32_e32 v74, v74
	v_exp_f32_e32 v75, v75
	v_exp_f32_e32 v76, v76
	v_exp_f32_e32 v77, v77
	v_exp_f32_e32 v78, v78
	v_exp_f32_e32 v79, v79
	v_exp_f32_e32 v80, v80
	v_exp_f32_e32 v81, v81
	v_exp_f32_e32 v82, v82
	v_exp_f32_e32 v83, v83
	v_exp_f32_e32 v84, v84
	v_exp_f32_e32 v85, v85
	v_pk_add_f32 v[64:65], v[64:65], 1.0 op_sel_hi:[1,0]
	v_pk_add_f32 v[68:69], v[68:69], 1.0 op_sel_hi:[1,0]
	v_pk_add_f32 v[74:75], v[74:75], 1.0 op_sel_hi:[1,0]
	v_pk_add_f32 v[76:77], v[76:77], 1.0 op_sel_hi:[1,0]
	v_pk_add_f32 v[78:79], v[78:79], 1.0 op_sel_hi:[1,0]
	v_pk_add_f32 v[80:81], v[80:81], 1.0 op_sel_hi:[1,0]
	v_pk_add_f32 v[82:83], v[82:83], 1.0 op_sel_hi:[1,0]
	v_pk_add_f32 v[84:85], v[84:85], 1.0 op_sel_hi:[1,0]
	v_rcp_f32_e32 v64, v64
	v_rcp_f32_e32 v65, v65
	v_rcp_f32_e32 v68, v68
	v_rcp_f32_e32 v69, v69
	v_rcp_f32_e32 v74, v74
	v_rcp_f32_e32 v75, v75
	v_rcp_f32_e32 v76, v76
	v_rcp_f32_e32 v77, v77
	v_rcp_f32_e32 v78, v78
	v_rcp_f32_e32 v79, v79
	v_rcp_f32_e32 v80, v80
	v_rcp_f32_e32 v81, v81
	v_rcp_f32_e32 v82, v82
	v_rcp_f32_e32 v83, v83
	v_rcp_f32_e32 v84, v84
	v_rcp_f32_e32 v85, v85
	v_pk_mul_f32 v[64:65], v[60:61], v[64:65]
	v_pk_mul_f32 v[68:69], v[62:63], v[68:69]
	v_pk_mul_f32 v[74:75], v[56:57], v[74:75]
	v_pk_mul_f32 v[76:77], v[58:59], v[76:77]
	v_pk_mul_f32 v[78:79], v[52:53], v[78:79]
	v_pk_mul_f32 v[80:81], v[54:55], v[80:81]
	v_pk_mul_f32 v[82:83], v[48:49], v[82:83]
	v_pk_mul_f32 v[84:85], v[50:51], v[84:85]
	v_pk_mul_f32 v[66:67], v[64:65], v[64:65]
	v_pk_mul_f32 v[70:71], v[68:69], v[68:69]
	v_add_f32_e32 v66, v66, v67
	v_add_f32_e32 v66, v70, v66
	v_pk_mul_f32 v[86:87], v[74:75], v[74:75]
	v_add_f32_e32 v66, v71, v66
	v_add_f32_e32 v66, v86, v66
	v_pk_mul_f32 v[88:89], v[76:77], v[76:77]
	v_add_f32_e32 v66, v87, v66
	v_add_f32_e32 v66, v88, v66
	v_pk_mul_f32 v[90:91], v[78:79], v[78:79]
	v_add_f32_e32 v66, v89, v66
	v_add_f32_e32 v66, v66, v90
	v_pk_mul_f32 v[92:93], v[80:81], v[80:81]
	v_add_f32_e32 v66, v91, v66
	v_add_f32_e32 v66, v92, v66
	v_pk_mul_f32 v[94:95], v[82:83], v[82:83]
	v_add_f32_e32 v66, v93, v66
	v_add_f32_e32 v66, v94, v66
	v_pk_mul_f32 v[96:97], v[84:85], v[84:85]
	v_add_f32_e32 v66, v95, v66
	v_add_f32_e32 v66, v96, v66
	v_add_f32_e32 v66, v97, v66
	ds_bpermute_b32 v67, v229, v66
	v_lshl_add_u64 v[96:97], v[140:141], 2, s[18:19]
	v_ashrrev_i32_e32 v73, 31, v72
	v_lshlrev_b64 v[90:91], 10, v[72:73]
	v_lshlrev_b32_e32 v88, 9, v72
	s_waitcnt lgkmcnt(0)
	v_add_f32_e32 v66, v66, v67
	ds_bpermute_b32 v67, v230, v66
	v_mov_b32_e32 v89, v141
	s_waitcnt lgkmcnt(0)
	v_add_f32_e32 v66, v66, v67
	v_fmamk_f32 v66, v66, 0x3c800000, v188
	v_cmp_gt_f32_e32 vcc, s13, v66
	v_mul_f32_e32 v67, 0x4b800000, v66
	s_nop 0
	v_cndmask_b32_e32 v66, v66, v67, vcc
	v_rsq_f32_e32 v66, v66
	s_nop 0
	v_mul_f32_e32 v67, 0x45800000, v66
	v_cndmask_b32_e32 v86, v66, v67, vcc
	v_pk_mul_f32 v[92:93], v[64:65], v[86:87] op_sel_hi:[1,0]
	v_pk_mul_f32 v[94:95], v[68:69], v[86:87] op_sel_hi:[1,0]
	global_load_dwordx4 v[64:67], v[96:97], off offset:16
	global_load_dwordx4 v[68:71], v[96:97], off
	v_pk_mul_f32 v[74:75], v[74:75], v[86:87] op_sel_hi:[1,0]
	v_pk_mul_f32 v[76:77], v[76:77], v[86:87] op_sel_hi:[1,0]
	s_waitcnt vmcnt(0)
	v_pk_mul_f32 v[64:65], v[64:65], v[74:75]
	v_lshl_add_u64 v[74:75], s[46:47], 0, v[90:91]
	v_pk_mul_f32 v[70:71], v[70:71], v[94:95]
	v_pk_mul_f32 v[68:69], v[68:69], v[92:93]
	v_pk_mul_f32 v[66:67], v[66:67], v[76:77]
	v_lshl_add_u64 v[76:77], v[140:141], 1, v[74:75]
	v_lshl_add_u64 v[74:75], v[88:89], 2, s[56:57]
	v_cvt_pk_bf16_f32 v90, v68, v69
	v_cvt_pk_bf16_f32 v91, v70, v71
	v_cvt_pk_bf16_f32 v92, v64, v65
	v_cvt_pk_bf16_f32 v93, v66, v67
	global_store_dwordx4 v[76:77], v[90:93], off
	s_and_saveexec_b64 s[0:1], s[10:11]
	s_cbranch_execz .LBB0_298
	v_lshl_add_u64 v[88:89], v[140:141], 2, v[74:75]
	v_lshl_add_u64 v[90:91], v[88:89], 0, s[70:71]
	v_add_co_u32_e32 v88, vcc, 0x2108000, v88
	s_nop 1
	v_addc_co_u32_e32 v89, vcc, 0, v89, vcc
	global_store_dwordx4 v[88:89], v[68:71], off
	global_store_dwordx4 v[90:91], v[64:67], off offset:16

; __device__ __forceinline__ float gelu_tanh(float x) { const float u = 1.5957691216f * (x + 0.044715f * x * x * x); return x * __builtin_amdgcn_rcpf(1.f + __expf(-u)); }
; __device__ __forceinline__ void st_bf16x8(bf16_t* p, const f32x4 a, const f32x4 b) { uint4 o; o.x = cvt_pk_bf16(a[0], a[1]); o.y = cvt_pk_bf16(a[2], a[3]); o.z = cvt_pk_bf16(b[0], b[1]); o.w = cvt_pk_bf16(b[2], b[3]); *(uint4*)p = o; }
;     __device__ __forceinline__ void row(const f32x4 (&a)[2][2], int row, int pn, int wc, int fq) const {
;         if (pn < 2 || pn == 4 || pn == 5) {
;             bf16_t* dst = (pn < 2 ? pU : pBG) + (size_t)row * 512 + (pn & 1) * 256 + wc * 32 + 8 * fq;
; #pragma unroll
;             for (int bj = 0; bj < 2; ++bj) { f32x4 v0 = a[bj][0], v1 = a[bj][1];
;                 if (pn < 2) {
; #pragma unroll
;                     for (int j = 0; j < 4; ++j) { v0[j] = gelu_tanh(v0[j]); v1[j] = gelu_tanh(v1[j]); } }
;                 st_bf16x8(dst + bj * HALF, v0, v1); }
.LBB0_302:
	s_and_b64 vcc, exec, s[4:5]
	s_cbranch_vccnz .LBB0_304
	v_mov_b32_e32 v190, 0x3d372713
	v_mov_b32_e32 v192, 0xbfcc422a
	v_mov_b32_e32 v194, 0x3fb8aa3b
	v_pk_mul_f32 v[196:197], v[56:57], v[190:191] op_sel_hi:[1,0]
	v_pk_mul_f32 v[198:199], v[58:59], v[190:191] op_sel_hi:[1,0]
	v_pk_mul_f32 v[200:201], v[60:61], v[190:191] op_sel_hi:[1,0]
	v_pk_mul_f32 v[202:203], v[62:63], v[190:191] op_sel_hi:[1,0]
	v_pk_mul_f32 v[196:197], v[56:57], v[196:197]
	v_pk_mul_f32 v[198:199], v[58:59], v[198:199]
	v_pk_mul_f32 v[200:201], v[60:61], v[200:201]
	v_pk_mul_f32 v[202:203], v[62:63], v[202:203]
	v_pk_fma_f32 v[196:197], v[56:57], v[196:197], v[56:57]
	v_pk_fma_f32 v[198:199], v[58:59], v[198:199], v[58:59]
	v_pk_fma_f32 v[200:201], v[60:61], v[200:201], v[60:61]
	v_pk_fma_f32 v[202:203], v[62:63], v[202:203], v[62:63]
	v_pk_mul_f32 v[196:197], v[196:197], v[192:193] op_sel_hi:[1,0]
	v_pk_mul_f32 v[198:199], v[198:199], v[192:193] op_sel_hi:[1,0]
	v_pk_mul_f32 v[200:201], v[200:201], v[192:193] op_sel_hi:[1,0]
	v_pk_mul_f32 v[202:203], v[202:203], v[192:193] op_sel_hi:[1,0]
	v_pk_mul_f32 v[196:197], v[196:197], v[194:195] op_sel_hi:[1,0]
	v_pk_mul_f32 v[198:199], v[198:199], v[194:195] op_sel_hi:[1,0]
	v_pk_mul_f32 v[200:201], v[200:201], v[194:195] op_sel_hi:[1,0]
	v_pk_mul_f32 v[202:203], v[202:203], v[194:195] op_sel_hi:[1,0]
	v_exp_f32_e32 v196, v196
	v_exp_f32_e32 v197, v197
	v_exp_f32_e32 v198, v198
	v_exp_f32_e32 v199, v199
	v_exp_f32_e32 v200, v200
	v_exp_f32_e32 v201, v201
	v_exp_f32_e32 v202, v202
	v_exp_f32_e32 v203, v203
	v_pk_add_f32 v[196:197], v[196:197], 1.0 op_sel_hi:[1,0]
	v_pk_add_f32 v[198:199], v[198:199], 1.0 op_sel_hi:[1,0]
	v_pk_add_f32 v[200:201], v[200:201], 1.0 op_sel_hi:[1,0]
	v_pk_add_f32 v[202:203], v[202:203], 1.0 op_sel_hi:[1,0]
	v_rcp_f32_e32 v196, v196
	v_rcp_f32_e32 v197, v197
	v_rcp_f32_e32 v198, v198
	v_rcp_f32_e32 v199, v199
	v_rcp_f32_e32 v200, v200
	v_rcp_f32_e32 v201, v201
	v_rcp_f32_e32 v202, v202
	v_rcp_f32_e32 v203, v203
	v_pk_mul_f32 v[56:57], v[56:57], v[196:197]
	v_pk_mul_f32 v[58:59], v[58:59], v[198:199]
	v_pk_mul_f32 v[60:61], v[60:61], v[200:201]
	v_pk_mul_f32 v[62:63], v[62:63], v[202:203]
	s_nop 0
	s_nop 0
	s_nop 0
	s_nop 0
.LBB0_304:
	s_and_b64 s[0:1], s[80:81], exec
	v_ashrrev_i32_e32 v73, 31, v72
	s_cselect_b32 s1, s31, s49
	s_cselect_b32 s0, s30, s48
	v_lshlrev_b64 v[64:65], 10, v[72:73]
	v_lshl_add_u64 v[64:65], s[0:1], 0, v[64:65]
	s_lshl_b32 s64, s61, 1
	v_lshl_add_u64 v[64:65], v[64:65], 0, s[64:65]
	s_lshl_b32 s64, s91, 1
	v_lshl_add_u64 v[64:65], v[64:65], 0, s[64:65]
	v_lshlrev_b32_e32 v66, 1, v142
	v_mov_b32_e32 v67, v141
	v_lshl_add_u64 v[64:65], v[64:65], 0, v[66:67]
	s_and_b64 vcc, exec, s[4:5]
	v_cvt_pk_bf16_f32 v60, v60, v61
	v_cvt_pk_bf16_f32 v61, v62, v63
	v_cvt_pk_bf16_f32 v62, v56, v57
	v_cvt_pk_bf16_f32 v63, v58, v59
	global_store_dwordx4 v[64:65], v[60:63], off
	s_cbranch_vccnz .LBB0_306
	v_mov_b32_e32 v190, 0x3d372713
	v_mov_b32_e32 v192, 0xbfcc422a
	v_mov_b32_e32 v194, 0x3fb8aa3b
	v_pk_mul_f32 v[196:197], v[48:49], v[190:191] op_sel_hi:[1,0]
	v_pk_mul_f32 v[198:199], v[50:51], v[190:191] op_sel_hi:[1,0]
	v_pk_mul_f32 v[200:201], v[52:53], v[190:191] op_sel_hi:[1,0]
	v_pk_mul_f32 v[202:203], v[54:55], v[190:191] op_sel_hi:[1,0]
	v_pk_mul_f32 v[196:197], v[48:49], v[196:197]
	v_pk_mul_f32 v[198:199], v[50:51], v[198:199]
	v_pk_mul_f32 v[200:201], v[52:53], v[200:201]
	v_pk_mul_f32 v[202:203], v[54:55], v[202:203]
	v_pk_fma_f32 v[196:197], v[48:49], v[196:197], v[48:49]
	v_pk_fma_f32 v[198:199], v[50:51], v[198:199], v[50:51]
	v_pk_fma_f32 v[200:201], v[52:53], v[200:201], v[52:53]
	v_pk_fma_f32 v[202:203], v[54:55], v[202:203], v[54:55]
	v_pk_mul_f32 v[196:197], v[196:197], v[192:193] op_sel_hi:[1,0]
	v_pk_mul_f32 v[198:199], v[198:199], v[192:193] op_sel_hi:[1,0]
	v_pk_mul_f32 v[200:201], v[200:201], v[192:193] op_sel_hi:[1,0]
	v_pk_mul_f32 v[202:203], v[202:203], v[192:193] op_sel_hi:[1,0]
	v_pk_mul_f32 v[196:197], v[196:197], v[194:195] op_sel_hi:[1,0]
	v_pk_mul_f32 v[198:199], v[198:199], v[194:195] op_sel_hi:[1,0]
	v_pk_mul_f32 v[200:201], v[200:201], v[194:195] op_sel_hi:[1,0]
	v_pk_mul_f32 v[202:203], v[202:203], v[194:195] op_sel_hi:[1,0]
	v_exp_f32_e32 v196, v196
	v_exp_f32_e32 v197, v197
	v_exp_f32_e32 v198, v198
	v_exp_f32_e32 v199, v199
	v_exp_f32_e32 v200, v200
	v_exp_f32_e32 v201, v201
	v_exp_f32_e32 v202, v202
	v_exp_f32_e32 v203, v203
	v_pk_add_f32 v[196:197], v[196:197], 1.0 op_sel_hi:[1,0]
	v_pk_add_f32 v[198:199], v[198:199], 1.0 op_sel_hi:[1,0]
	v_pk_add_f32 v[200:201], v[200:201], 1.0 op_sel_hi:[1,0]
	v_pk_add_f32 v[202:203], v[202:203], 1.0 op_sel_hi:[1,0]
	v_rcp_f32_e32 v196, v196
	v_rcp_f32_e32 v197, v197
	v_rcp_f32_e32 v198, v198
	v_rcp_f32_e32 v199, v199
	v_rcp_f32_e32 v200, v200
	v_rcp_f32_e32 v201, v201
	v_rcp_f32_e32 v202, v202
	v_rcp_f32_e32 v203, v203
	v_pk_mul_f32 v[48:49], v[48:49], v[196:197]
	v_pk_mul_f32 v[50:51], v[50:51], v[198:199]
	v_pk_mul_f32 v[52:53], v[52:53], v[200:201]
	v_pk_mul_f32 v[54:55], v[54:55], v[202:203]
	s_nop 0
	s_nop 0
	s_nop 0
	s_nop 0

; __device__ __forceinline__ float gelu_tanh(float x) { const float u = 1.5957691216f * (x + 0.044715f * x * x * x); return x * __builtin_amdgcn_rcpf(1.f + __expf(-u)); }
; __device__ __forceinline__ void st_bf16x8(bf16_t* p, const f32x4 a, const f32x4 b) { uint4 o; o.x = cvt_pk_bf16(a[0], a[1]); o.y = cvt_pk_bf16(a[2], a[3]); o.z = cvt_pk_bf16(b[0], b[1]); o.w = cvt_pk_bf16(b[2], b[3]); *(uint4*)p = o; }
;     __device__ __forceinline__ void row(const f32x4 (&a)[2][2], int row, int pn, int wc, int fq) const {
;     ...
;             const int head = (pn - 2) * 4 + wc;
;             f32x4 g[2][2]; float ss = 0.f;
; #pragma unroll
;             for (int bj = 0; bj < 2; ++bj)
; #pragma unroll
;                 for (int n = 0; n < 2; ++n)
; #pragma unroll
;                     for (int j = 0; j < 4; ++j) { const float t = gelu_tanh(a[bj][n][j]); g[bj][n][j] = t; ss += t * t; }
;             ss += __shfl_xor(ss, 16); ss += __shfl_xor(ss, 32);
;             const float rs = rsqrtf(ss * (1.f / 64.f) + EPS);
; #pragma unroll
;             for (int bj = 0; bj < 2; ++bj) { const int d = head * 64 + bj * 32 + 8 * fq;
;                 const f32x4 v0 = g[bj][0] * rs * *(const f32x4*)(g_v + d), v1 = g[bj][1] * rs * *(const f32x4*)(g_v + d + 4);
;                 st_bf16x8(pV + (size_t)row * 512 + d, v0, v1);
;                 if (row >= NP && row < NTOK) { float* o = out + O_VS + (size_t)(row - NP) * 512 + d; *(f32x4*)o = v0; *(f32x4*)(o + 4) = v1; } }
.LBB0_311:
	s_andn2_b64 vcc, exec, s[0:1]
	s_cbranch_vccnz .LBB0_317
	v_mov_b32_e32 v190, 0x3d372713
	v_mov_b32_e32 v192, 0xbfcc422a
	v_mov_b32_e32 v194, 0x3fb8aa3b
	v_pk_mul_f32 v[48:49], v[44:45], v[190:191] op_sel_hi:[1,0]
	v_pk_mul_f32 v[52:53], v[46:47], v[190:191] op_sel_hi:[1,0]
	v_pk_mul_f32 v[58:59], v[40:41], v[190:191] op_sel_hi:[1,0]
	v_pk_mul_f32 v[60:61], v[42:43], v[190:191] op_sel_hi:[1,0]
	v_pk_mul_f32 v[62:63], v[36:37], v[190:191] op_sel_hi:[1,0]
	v_pk_mul_f32 v[64:65], v[38:39], v[190:191] op_sel_hi:[1,0]
	v_pk_mul_f32 v[66:67], v[32:33], v[190:191] op_sel_hi:[1,0]
	v_pk_mul_f32 v[68:69], v[34:35], v[190:191] op_sel_hi:[1,0]
	v_pk_mul_f32 v[48:49], v[44:45], v[48:49]
	v_pk_mul_f32 v[52:53], v[46:47], v[52:53]
	v_pk_mul_f32 v[58:59], v[40:41], v[58:59]
	v_pk_mul_f32 v[60:61], v[42:43], v[60:61]
	v_pk_mul_f32 v[62:63], v[36:37], v[62:63]
	v_pk_mul_f32 v[64:65], v[38:39], v[64:65]
	v_pk_mul_f32 v[66:67], v[32:33], v[66:67]
	v_pk_mul_f32 v[68:69], v[34:35], v[68:69]
	v_pk_fma_f32 v[48:49], v[44:45], v[48:49], v[44:45]
	v_pk_fma_f32 v[52:53], v[46:47], v[52:53], v[46:47]
	v_pk_fma_f32 v[58:59], v[40:41], v[58:59], v[40:41]
	v_pk_fma_f32 v[60:61], v[42:43], v[60:61], v[42:43]
	v_pk_fma_f32 v[62:63], v[36:37], v[62:63], v[36:37]
	v_pk_fma_f32 v[64:65], v[38:39], v[64:65], v[38:39]
	v_pk_fma_f32 v[66:67], v[32:33], v[66:67], v[32:33]
	v_pk_fma_f32 v[68:69], v[34:35], v[68:69], v[34:35]
	v_pk_mul_f32 v[48:49], v[48:49], v[192:193] op_sel_hi:[1,0]
	v_pk_mul_f32 v[52:53], v[52:53], v[192:193] op_sel_hi:[1,0]
	v_pk_mul_f32 v[58:59], v[58:59], v[192:193] op_sel_hi:[1,0]
	v_pk_mul_f32 v[60:61], v[60:61], v[192:193] op_sel_hi:[1,0]
	v_pk_mul_f32 v[62:63], v[62:63], v[192:193] op_sel_hi:[1,0]
	v_pk_mul_f32 v[64:65], v[64:65], v[192:193] op_sel_hi:[1,0]
	v_pk_mul_f32 v[66:67], v[66:67], v[192:193] op_sel_hi:[1,0]
	v_pk_mul_f32 v[68:69], v[68:69], v[192:193] op_sel_hi:[1,0]
	v_pk_mul_f32 v[48:49], v[48:49], v[194:195] op_sel_hi:[1,0]
	v_pk_mul_f32 v[52:53], v[52:53], v[194:195] op_sel_hi:[1,0]
	v_pk_mul_f32 v[58:59], v[58:59], v[194:195] op_sel_hi:[1,0]
	v_pk_mul_f32 v[60:61], v[60:61], v[194:195] op_sel_hi:[1,0]
	v_pk_mul_f32 v[62:63], v[62:63], v[194:195] op_sel_hi:[1,0]
	v_pk_mul_f32 v[64:65], v[64:65], v[194:195] op_sel_hi:[1,0]
	v_pk_mul_f32 v[66:67], v[66:67], v[194:195] op_sel_hi:[1,0]
	v_pk_mul_f32 v[68:69], v[68:69], v[194:195] op_sel_hi:[1,0]
	v_exp_f32_e32 v48, v48
	v_exp_f32_e32 v49, v49
	v_exp_f32_e32 v52, v52
	v_exp_f32_e32 v53, v53
	v_exp_f32_e32 v58, v58
	v_exp_f32_e32 v59, v59
	v_exp_f32_e32 v60, v60
	v_exp_f32_e32 v61, v61
	v_exp_f32_e32 v62, v62
	v_exp_f32_e32 v63, v63
	v_exp_f32_e32 v64, v64
	v_exp_f32_e32 v65, v65
	v_exp_f32_e32 v66, v66
	v_exp_f32_e32 v67, v67
	v_exp_f32_e32 v68, v68
	v_exp_f32_e32 v69, v69
	v_pk_add_f32 v[48:49], v[48:49], 1.0 op_sel_hi:[1,0]
	v_pk_add_f32 v[52:53], v[52:53], 1.0 op_sel_hi:[1,0]
	v_pk_add_f32 v[58:59], v[58:59], 1.0 op_sel_hi:[1,0]
	v_pk_add_f32 v[60:61], v[60:61], 1.0 op_sel_hi:[1,0]
	v_pk_add_f32 v[62:63], v[62:63], 1.0 op_sel_hi:[1,0]
	v_pk_add_f32 v[64:65], v[64:65], 1.0 op_sel_hi:[1,0]
	v_pk_add_f32 v[66:67], v[66:67], 1.0 op_sel_hi:[1,0]
	v_pk_add_f32 v[68:69], v[68:69], 1.0 op_sel_hi:[1,0]
	v_rcp_f32_e32 v48, v48
	v_rcp_f32_e32 v49, v49
	v_rcp_f32_e32 v52, v52
	v_rcp_f32_e32 v53, v53
	v_rcp_f32_e32 v58, v58
	v_rcp_f32_e32 v59, v59
	v_rcp_f32_e32 v60, v60
	v_rcp_f32_e32 v61, v61
	v_rcp_f32_e32 v62, v62
	v_rcp_f32_e32 v63, v63
	v_rcp_f32_e32 v64, v64
	v_rcp_f32_e32 v65, v65
	v_rcp_f32_e32 v66, v66
	v_rcp_f32_e32 v67, v67
	v_rcp_f32_e32 v68, v68
	v_rcp_f32_e32 v69, v69
	v_pk_mul_f32 v[48:49], v[44:45], v[48:49]
	v_pk_mul_f32 v[52:53], v[46:47], v[52:53]
	v_pk_mul_f32 v[58:59], v[40:41], v[58:59]
	v_pk_mul_f32 v[60:61], v[42:43], v[60:61]
	v_pk_mul_f32 v[62:63], v[36:37], v[62:63]
	v_pk_mul_f32 v[64:65], v[38:39], v[64:65]
	v_pk_mul_f32 v[66:67], v[32:33], v[66:67]
	v_pk_mul_f32 v[68:69], v[34:35], v[68:69]
	v_pk_mul_f32 v[50:51], v[48:49], v[48:49]
	v_pk_mul_f32 v[54:55], v[52:53], v[52:53]
	v_add_f32_e32 v50, v50, v51
	v_add_f32_e32 v50, v54, v50
	v_pk_mul_f32 v[70:71], v[58:59], v[58:59]
	v_add_f32_e32 v50, v55, v50
	v_add_f32_e32 v50, v70, v50
	v_pk_mul_f32 v[74:75], v[60:61], v[60:61]
	v_add_f32_e32 v50, v71, v50
	v_add_f32_e32 v50, v74, v50
	v_pk_mul_f32 v[76:77], v[62:63], v[62:63]
	v_add_f32_e32 v50, v75, v50
	v_add_f32_e32 v50, v50, v76
	v_pk_mul_f32 v[78:79], v[64:65], v[64:65]
	v_add_f32_e32 v50, v77, v50
	v_add_f32_e32 v50, v78, v50
	v_pk_mul_f32 v[80:81], v[66:67], v[66:67]
	v_add_f32_e32 v50, v79, v50
	v_add_f32_e32 v50, v80, v50
	v_pk_mul_f32 v[82:83], v[68:69], v[68:69]
	v_add_f32_e32 v50, v81, v50
	v_add_f32_e32 v50, v82, v50
	v_add_f32_e32 v50, v83, v50
	ds_bpermute_b32 v51, v229, v50
	v_lshl_add_u64 v[82:83], v[140:141], 2, s[18:19]
	v_ashrrev_i32_e32 v57, 31, v56
	v_lshlrev_b64 v[76:77], 10, v[56:57]
	v_lshlrev_b32_e32 v74, 9, v56
	s_waitcnt lgkmcnt(0)
	v_add_f32_e32 v50, v50, v51
	ds_bpermute_b32 v51, v230, v50
	v_mov_b32_e32 v75, v141
	s_waitcnt lgkmcnt(0)
	v_add_f32_e32 v50, v50, v51
	v_fmamk_f32 v50, v50, 0x3c800000, v188
	v_cmp_gt_f32_e32 vcc, s13, v50
	v_mul_f32_e32 v51, 0x4b800000, v50
	s_nop 0
	v_cndmask_b32_e32 v50, v50, v51, vcc
	v_rsq_f32_e32 v50, v50
	s_nop 0
	v_mul_f32_e32 v51, 0x45800000, v50
	v_cndmask_b32_e32 v70, v50, v51, vcc
	v_pk_mul_f32 v[78:79], v[48:49], v[70:71] op_sel_hi:[1,0]
	v_pk_mul_f32 v[80:81], v[52:53], v[70:71] op_sel_hi:[1,0]
	global_load_dwordx4 v[48:51], v[82:83], off offset:16
	global_load_dwordx4 v[52:55], v[82:83], off
	v_pk_mul_f32 v[58:59], v[58:59], v[70:71] op_sel_hi:[1,0]
	v_pk_mul_f32 v[60:61], v[60:61], v[70:71] op_sel_hi:[1,0]
	s_waitcnt vmcnt(0)
	v_pk_mul_f32 v[48:49], v[48:49], v[58:59]
	v_lshl_add_u64 v[58:59], s[46:47], 0, v[76:77]
	v_pk_mul_f32 v[54:55], v[54:55], v[80:81]
	v_pk_mul_f32 v[52:53], v[52:53], v[78:79]
	v_pk_mul_f32 v[50:51], v[50:51], v[60:61]
	v_lshl_add_u64 v[60:61], v[140:141], 1, v[58:59]
	v_lshl_add_u64 v[58:59], v[74:75], 2, s[56:57]
	v_cvt_pk_bf16_f32 v76, v52, v53
	v_cvt_pk_bf16_f32 v77, v54, v55
	v_cvt_pk_bf16_f32 v78, v48, v49
	v_cvt_pk_bf16_f32 v79, v50, v51
	global_store_dwordx4 v[60:61], v[76:79], off
	s_and_saveexec_b64 s[0:1], s[10:11]
	s_cbranch_execz .LBB0_314
	v_lshl_add_u64 v[74:75], v[140:141], 2, v[58:59]
	v_lshl_add_u64 v[76:77], v[74:75], 0, s[70:71]
	v_add_co_u32_e32 v74, vcc, 0x2108000, v74
	s_nop 1
	v_addc_co_u32_e32 v75, vcc, 0, v75, vcc
	global_store_dwordx4 v[74:75], v[52:55], off
	global_store_dwordx4 v[76:77], v[48:51], off offset:16

; __device__ __forceinline__ float gelu_tanh(float x) { const float u = 1.5957691216f * (x + 0.044715f * x * x * x); return x * __builtin_amdgcn_rcpf(1.f + __expf(-u)); }
; __device__ __forceinline__ void st_bf16x8(bf16_t* p, const f32x4 a, const f32x4 b) { uint4 o; o.x = cvt_pk_bf16(a[0], a[1]); o.y = cvt_pk_bf16(a[2], a[3]); o.z = cvt_pk_bf16(b[0], b[1]); o.w = cvt_pk_bf16(b[2], b[3]); *(uint4*)p = o; }
;     __device__ __forceinline__ void row(const f32x4 (&a)[2][2], int row, int pn, int wc, int fq) const {
;         if (pn < 2 || pn == 4 || pn == 5) {
;             bf16_t* dst = (pn < 2 ? pU : pBG) + (size_t)row * 512 + (pn & 1) * 256 + wc * 32 + 8 * fq;
; #pragma unroll
;             for (int bj = 0; bj < 2; ++bj) { f32x4 v0 = a[bj][0], v1 = a[bj][1];
;                 if (pn < 2) {
; #pragma unroll
;                     for (int j = 0; j < 4; ++j) { v0[j] = gelu_tanh(v0[j]); v1[j] = gelu_tanh(v1[j]); } }
;                 st_bf16x8(dst + bj * HALF, v0, v1); }
.LBB0_318:
	s_and_b64 vcc, exec, s[4:5]
	s_cbranch_vccnz .LBB0_320
	v_mov_b32_e32 v190, 0x3d372713
	v_mov_b32_e32 v192, 0xbfcc422a
	v_mov_b32_e32 v194, 0x3fb8aa3b
	v_pk_mul_f32 v[196:197], v[40:41], v[190:191] op_sel_hi:[1,0]
	v_pk_mul_f32 v[198:199], v[42:43], v[190:191] op_sel_hi:[1,0]
	v_pk_mul_f32 v[200:201], v[44:45], v[190:191] op_sel_hi:[1,0]
	v_pk_mul_f32 v[202:203], v[46:47], v[190:191] op_sel_hi:[1,0]
	v_pk_mul_f32 v[196:197], v[40:41], v[196:197]
	v_pk_mul_f32 v[198:199], v[42:43], v[198:199]
	v_pk_mul_f32 v[200:201], v[44:45], v[200:201]
	v_pk_mul_f32 v[202:203], v[46:47], v[202:203]
	v_pk_fma_f32 v[196:197], v[40:41], v[196:197], v[40:41]
	v_pk_fma_f32 v[198:199], v[42:43], v[198:199], v[42:43]
	v_pk_fma_f32 v[200:201], v[44:45], v[200:201], v[44:45]
	v_pk_fma_f32 v[202:203], v[46:47], v[202:203], v[46:47]
	v_pk_mul_f32 v[196:197], v[196:197], v[192:193] op_sel_hi:[1,0]
	v_pk_mul_f32 v[198:199], v[198:199], v[192:193] op_sel_hi:[1,0]
	v_pk_mul_f32 v[200:201], v[200:201], v[192:193] op_sel_hi:[1,0]
	v_pk_mul_f32 v[202:203], v[202:203], v[192:193] op_sel_hi:[1,0]
	v_pk_mul_f32 v[196:197], v[196:197], v[194:195] op_sel_hi:[1,0]
	v_pk_mul_f32 v[198:199], v[198:199], v[194:195] op_sel_hi:[1,0]
	v_pk_mul_f32 v[200:201], v[200:201], v[194:195] op_sel_hi:[1,0]
	v_pk_mul_f32 v[202:203], v[202:203], v[194:195] op_sel_hi:[1,0]
	v_exp_f32_e32 v196, v196
	v_exp_f32_e32 v197, v197
	v_exp_f32_e32 v198, v198
	v_exp_f32_e32 v199, v199
	v_exp_f32_e32 v200, v200
	v_exp_f32_e32 v201, v201
	v_exp_f32_e32 v202, v202
	v_exp_f32_e32 v203, v203
	v_pk_add_f32 v[196:197], v[196:197], 1.0 op_sel_hi:[1,0]
	v_pk_add_f32 v[198:199], v[198:199], 1.0 op_sel_hi:[1,0]
	v_pk_add_f32 v[200:201], v[200:201], 1.0 op_sel_hi:[1,0]
	v_pk_add_f32 v[202:203], v[202:203], 1.0 op_sel_hi:[1,0]
	v_rcp_f32_e32 v196, v196
	v_rcp_f32_e32 v197, v197
	v_rcp_f32_e32 v198, v198
	v_rcp_f32_e32 v199, v199
	v_rcp_f32_e32 v200, v200
	v_rcp_f32_e32 v201, v201
	v_rcp_f32_e32 v202, v202
	v_rcp_f32_e32 v203, v203
	v_pk_mul_f32 v[40:41], v[40:41], v[196:197]
	v_pk_mul_f32 v[42:43], v[42:43], v[198:199]
	v_pk_mul_f32 v[44:45], v[44:45], v[200:201]
	v_pk_mul_f32 v[46:47], v[46:47], v[202:203]
	s_nop 0
	s_nop 0
	s_nop 0
	s_nop 0
.LBB0_320:
	s_and_b64 s[0:1], s[80:81], exec
	v_ashrrev_i32_e32 v57, 31, v56
	s_cselect_b32 s1, s31, s49
	s_cselect_b32 s0, s30, s48
	v_lshlrev_b64 v[48:49], 10, v[56:57]
	v_lshl_add_u64 v[48:49], s[0:1], 0, v[48:49]
	s_lshl_b32 s64, s61, 1
	v_lshl_add_u64 v[48:49], v[48:49], 0, s[64:65]
	s_lshl_b32 s64, s91, 1
	v_lshl_add_u64 v[48:49], v[48:49], 0, s[64:65]
	v_lshlrev_b32_e32 v50, 1, v142
	v_mov_b32_e32 v51, v141
	v_lshl_add_u64 v[48:49], v[48:49], 0, v[50:51]
	s_and_b64 vcc, exec, s[4:5]
	v_cvt_pk_bf16_f32 v44, v44, v45
	v_cvt_pk_bf16_f32 v45, v46, v47
	v_cvt_pk_bf16_f32 v46, v40, v41
	v_cvt_pk_bf16_f32 v47, v42, v43
	global_store_dwordx4 v[48:49], v[44:47], off
	s_cbranch_vccnz .LBB0_322
	v_mov_b32_e32 v190, 0x3d372713
	v_mov_b32_e32 v192, 0xbfcc422a
	v_mov_b32_e32 v194, 0x3fb8aa3b
	v_pk_mul_f32 v[196:197], v[32:33], v[190:191] op_sel_hi:[1,0]
	v_pk_mul_f32 v[198:199], v[34:35], v[190:191] op_sel_hi:[1,0]
	v_pk_mul_f32 v[200:201], v[36:37], v[190:191] op_sel_hi:[1,0]
	v_pk_mul_f32 v[202:203], v[38:39], v[190:191] op_sel_hi:[1,0]
	v_pk_mul_f32 v[196:197], v[32:33], v[196:197]
	v_pk_mul_f32 v[198:199], v[34:35], v[198:199]
	v_pk_mul_f32 v[200:201], v[36:37], v[200:201]
	v_pk_mul_f32 v[202:203], v[38:39], v[202:203]
	v_pk_fma_f32 v[196:197], v[32:33], v[196:197], v[32:33]
	v_pk_fma_f32 v[198:199], v[34:35], v[198:199], v[34:35]
	v_pk_fma_f32 v[200:201], v[36:37], v[200:201], v[36:37]
	v_pk_fma_f32 v[202:203], v[38:39], v[202:203], v[38:39]
	v_pk_mul_f32 v[196:197], v[196:197], v[192:193] op_sel_hi:[1,0]
	v_pk_mul_f32 v[198:199], v[198:199], v[192:193] op_sel_hi:[1,0]
	v_pk_mul_f32 v[200:201], v[200:201], v[192:193] op_sel_hi:[1,0]
	v_pk_mul_f32 v[202:203], v[202:203], v[192:193] op_sel_hi:[1,0]
	v_pk_mul_f32 v[196:197], v[196:197], v[194:195] op_sel_hi:[1,0]
	v_pk_mul_f32 v[198:199], v[198:199], v[194:195] op_sel_hi:[1,0]
	v_pk_mul_f32 v[200:201], v[200:201], v[194:195] op_sel_hi:[1,0]
	v_pk_mul_f32 v[202:203], v[202:203], v[194:195] op_sel_hi:[1,0]
	v_exp_f32_e32 v196, v196
	v_exp_f32_e32 v197, v197
	v_exp_f32_e32 v198, v198
	v_exp_f32_e32 v199, v199
	v_exp_f32_e32 v200, v200
	v_exp_f32_e32 v201, v201
	v_exp_f32_e32 v202, v202
	v_exp_f32_e32 v203, v203
	v_pk_add_f32 v[196:197], v[196:197], 1.0 op_sel_hi:[1,0]
	v_pk_add_f32 v[198:199], v[198:199], 1.0 op_sel_hi:[1,0]
	v_pk_add_f32 v[200:201], v[200:201], 1.0 op_sel_hi:[1,0]
	v_pk_add_f32 v[202:203], v[202:203], 1.0 op_sel_hi:[1,0]
	v_rcp_f32_e32 v196, v196
	v_rcp_f32_e32 v197, v197
	v_rcp_f32_e32 v198, v198
	v_rcp_f32_e32 v199, v199
	v_rcp_f32_e32 v200, v200
	v_rcp_f32_e32 v201, v201
	v_rcp_f32_e32 v202, v202
	v_rcp_f32_e32 v203, v203
	v_pk_mul_f32 v[32:33], v[32:33], v[196:197]
	v_pk_mul_f32 v[34:35], v[34:35], v[198:199]
	v_pk_mul_f32 v[36:37], v[36:37], v[200:201]
	v_pk_mul_f32 v[38:39], v[38:39], v[202:203]
	s_nop 0
	s_nop 0
	s_nop 0
	s_nop 0

; __device__ __forceinline__ float gelu_tanh(float x) { const float u = 1.5957691216f * (x + 0.044715f * x * x * x); return x * __builtin_amdgcn_rcpf(1.f + __expf(-u)); }
; __device__ __forceinline__ void st_bf16x8(bf16_t* p, const f32x4 a, const f32x4 b) { uint4 o; o.x = cvt_pk_bf16(a[0], a[1]); o.y = cvt_pk_bf16(a[2], a[3]); o.z = cvt_pk_bf16(b[0], b[1]); o.w = cvt_pk_bf16(b[2], b[3]); *(uint4*)p = o; }
;     __device__ __forceinline__ void row(const f32x4 (&a)[2][2], int row, int pn, int wc, int fq) const {
;     ...
;             const int head = (pn - 2) * 4 + wc;
;             f32x4 g[2][2]; float ss = 0.f;
; #pragma unroll
;             for (int bj = 0; bj < 2; ++bj)
; #pragma unroll
;                 for (int n = 0; n < 2; ++n)
; #pragma unroll
;                     for (int j = 0; j < 4; ++j) { const float t = gelu_tanh(a[bj][n][j]); g[bj][n][j] = t; ss += t * t; }
;             ss += __shfl_xor(ss, 16); ss += __shfl_xor(ss, 32);
;             const float rs = rsqrtf(ss * (1.f / 64.f) + EPS);
; #pragma unroll
;             for (int bj = 0; bj < 2; ++bj) { const int d = head * 64 + bj * 32 + 8 * fq;
;                 const f32x4 v0 = g[bj][0] * rs * *(const f32x4*)(g_v + d), v1 = g[bj][1] * rs * *(const f32x4*)(g_v + d + 4);
;                 st_bf16x8(pV + (size_t)row * 512 + d, v0, v1);
;                 if (row >= NP && row < NTOK) { float* o = out + O_VS + (size_t)(row - NP) * 512 + d; *(f32x4*)o = v0; *(f32x4*)(o + 4) = v1; } }
.LBB0_327:
	s_andn2_b64 vcc, exec, s[0:1]
	s_cbranch_vccnz .LBB0_333
	v_mov_b32_e32 v190, 0x3d372713
	v_mov_b32_e32 v192, 0xbfcc422a
	v_mov_b32_e32 v194, 0x3fb8aa3b
	v_pk_mul_f32 v[32:33], v[28:29], v[190:191] op_sel_hi:[1,0]
	v_pk_mul_f32 v[36:37], v[30:31], v[190:191] op_sel_hi:[1,0]
	v_pk_mul_f32 v[42:43], v[24:25], v[190:191] op_sel_hi:[1,0]
	v_pk_mul_f32 v[44:45], v[26:27], v[190:191] op_sel_hi:[1,0]
	v_pk_mul_f32 v[46:47], v[20:21], v[190:191] op_sel_hi:[1,0]
	v_pk_mul_f32 v[48:49], v[22:23], v[190:191] op_sel_hi:[1,0]
	v_pk_mul_f32 v[50:51], v[16:17], v[190:191] op_sel_hi:[1,0]
	v_pk_mul_f32 v[52:53], v[18:19], v[190:191] op_sel_hi:[1,0]
	v_pk_mul_f32 v[32:33], v[28:29], v[32:33]
	v_pk_mul_f32 v[36:37], v[30:31], v[36:37]
	v_pk_mul_f32 v[42:43], v[24:25], v[42:43]
	v_pk_mul_f32 v[44:45], v[26:27], v[44:45]
	v_pk_mul_f32 v[46:47], v[20:21], v[46:47]
	v_pk_mul_f32 v[48:49], v[22:23], v[48:49]
	v_pk_mul_f32 v[50:51], v[16:17], v[50:51]
	v_pk_mul_f32 v[52:53], v[18:19], v[52:53]
	v_pk_fma_f32 v[32:33], v[28:29], v[32:33], v[28:29]
	v_pk_fma_f32 v[36:37], v[30:31], v[36:37], v[30:31]
	v_pk_fma_f32 v[42:43], v[24:25], v[42:43], v[24:25]
	v_pk_fma_f32 v[44:45], v[26:27], v[44:45], v[26:27]
	v_pk_fma_f32 v[46:47], v[20:21], v[46:47], v[20:21]
	v_pk_fma_f32 v[48:49], v[22:23], v[48:49], v[22:23]
	v_pk_fma_f32 v[50:51], v[16:17], v[50:51], v[16:17]
	v_pk_fma_f32 v[52:53], v[18:19], v[52:53], v[18:19]
	v_pk_mul_f32 v[32:33], v[32:33], v[192:193] op_sel_hi:[1,0]
	v_pk_mul_f32 v[36:37], v[36:37], v[192:193] op_sel_hi:[1,0]
	v_pk_mul_f32 v[42:43], v[42:43], v[192:193] op_sel_hi:[1,0]
	v_pk_mul_f32 v[44:45], v[44:45], v[192:193] op_sel_hi:[1,0]
	v_pk_mul_f32 v[46:47], v[46:47], v[192:193] op_sel_hi:[1,0]
	v_pk_mul_f32 v[48:49], v[48:49], v[192:193] op_sel_hi:[1,0]
	v_pk_mul_f32 v[50:51], v[50:51], v[192:193] op_sel_hi:[1,0]
	v_pk_mul_f32 v[52:53], v[52:53], v[192:193] op_sel_hi:[1,0]
	v_pk_mul_f32 v[32:33], v[32:33], v[194:195] op_sel_hi:[1,0]
	v_pk_mul_f32 v[36:37], v[36:37], v[194:195] op_sel_hi:[1,0]
	v_pk_mul_f32 v[42:43], v[42:43], v[194:195] op_sel_hi:[1,0]
	v_pk_mul_f32 v[44:45], v[44:45], v[194:195] op_sel_hi:[1,0]
	v_pk_mul_f32 v[46:47], v[46:47], v[194:195] op_sel_hi:[1,0]
	v_pk_mul_f32 v[48:49], v[48:49], v[194:195] op_sel_hi:[1,0]
	v_pk_mul_f32 v[50:51], v[50:51], v[194:195] op_sel_hi:[1,0]
	v_pk_mul_f32 v[52:53], v[52:53], v[194:195] op_sel_hi:[1,0]
	v_exp_f32_e32 v32, v32
	v_exp_f32_e32 v33, v33
	v_exp_f32_e32 v36, v36
	v_exp_f32_e32 v37, v37
	v_exp_f32_e32 v42, v42
	v_exp_f32_e32 v43, v43
	v_exp_f32_e32 v44, v44
	v_exp_f32_e32 v45, v45
	v_exp_f32_e32 v46, v46
	v_exp_f32_e32 v47, v47
	v_exp_f32_e32 v48, v48
	v_exp_f32_e32 v49, v49
	v_exp_f32_e32 v50, v50
	v_exp_f32_e32 v51, v51
	v_exp_f32_e32 v52, v52
	v_exp_f32_e32 v53, v53
	v_pk_add_f32 v[32:33], v[32:33], 1.0 op_sel_hi:[1,0]
	v_pk_add_f32 v[36:37], v[36:37], 1.0 op_sel_hi:[1,0]
	v_pk_add_f32 v[42:43], v[42:43], 1.0 op_sel_hi:[1,0]
	v_pk_add_f32 v[44:45], v[44:45], 1.0 op_sel_hi:[1,0]
	v_pk_add_f32 v[46:47], v[46:47], 1.0 op_sel_hi:[1,0]
	v_pk_add_f32 v[48:49], v[48:49], 1.0 op_sel_hi:[1,0]
	v_pk_add_f32 v[50:51], v[50:51], 1.0 op_sel_hi:[1,0]
	v_pk_add_f32 v[52:53], v[52:53], 1.0 op_sel_hi:[1,0]
	v_rcp_f32_e32 v32, v32
	v_rcp_f32_e32 v33, v33
	v_rcp_f32_e32 v36, v36
	v_rcp_f32_e32 v37, v37
	v_rcp_f32_e32 v42, v42
	v_rcp_f32_e32 v43, v43
	v_rcp_f32_e32 v44, v44
	v_rcp_f32_e32 v45, v45
	v_rcp_f32_e32 v46, v46
	v_rcp_f32_e32 v47, v47
	v_rcp_f32_e32 v48, v48
	v_rcp_f32_e32 v49, v49
	v_rcp_f32_e32 v50, v50
	v_rcp_f32_e32 v51, v51
	v_rcp_f32_e32 v52, v52
	v_rcp_f32_e32 v53, v53
	v_pk_mul_f32 v[32:33], v[28:29], v[32:33]
	v_pk_mul_f32 v[36:37], v[30:31], v[36:37]
	v_pk_mul_f32 v[42:43], v[24:25], v[42:43]
	v_pk_mul_f32 v[44:45], v[26:27], v[44:45]
	v_pk_mul_f32 v[46:47], v[20:21], v[46:47]
	v_pk_mul_f32 v[48:49], v[22:23], v[48:49]
	v_pk_mul_f32 v[50:51], v[16:17], v[50:51]
	v_pk_mul_f32 v[52:53], v[18:19], v[52:53]
	v_pk_mul_f32 v[34:35], v[32:33], v[32:33]
	v_pk_mul_f32 v[38:39], v[36:37], v[36:37]
	v_add_f32_e32 v34, v34, v35
	v_add_f32_e32 v34, v38, v34
	v_pk_mul_f32 v[54:55], v[42:43], v[42:43]
	v_add_f32_e32 v34, v39, v34
	v_add_f32_e32 v34, v54, v34
	v_pk_mul_f32 v[56:57], v[44:45], v[44:45]
	v_add_f32_e32 v34, v55, v34
	v_add_f32_e32 v34, v56, v34
	v_pk_mul_f32 v[58:59], v[46:47], v[46:47]
	v_add_f32_e32 v34, v57, v34
	v_add_f32_e32 v34, v34, v58
	v_pk_mul_f32 v[60:61], v[48:49], v[48:49]
	v_add_f32_e32 v34, v59, v34
	v_add_f32_e32 v34, v60, v34
	v_pk_mul_f32 v[62:63], v[50:51], v[50:51]
	v_add_f32_e32 v34, v61, v34
	v_add_f32_e32 v34, v62, v34
	v_pk_mul_f32 v[64:65], v[52:53], v[52:53]
	v_add_f32_e32 v34, v63, v34
	v_add_f32_e32 v34, v64, v34
	v_add_f32_e32 v34, v65, v34
	ds_bpermute_b32 v35, v229, v34
	v_lshl_add_u64 v[64:65], v[140:141], 2, s[18:19]
	v_ashrrev_i32_e32 v41, 31, v40
	v_lshlrev_b64 v[58:59], 10, v[40:41]
	v_lshlrev_b32_e32 v56, 9, v40
	s_waitcnt lgkmcnt(0)
	v_add_f32_e32 v34, v34, v35
	ds_bpermute_b32 v35, v230, v34
	v_mov_b32_e32 v57, v141
	s_waitcnt lgkmcnt(0)
	v_add_f32_e32 v34, v34, v35
	v_fmamk_f32 v34, v34, 0x3c800000, v188
	v_cmp_gt_f32_e32 vcc, s13, v34
	v_mul_f32_e32 v35, 0x4b800000, v34
	s_nop 0
	v_cndmask_b32_e32 v34, v34, v35, vcc
	v_rsq_f32_e32 v34, v34
	s_nop 0
	v_mul_f32_e32 v35, 0x45800000, v34
	v_cndmask_b32_e32 v54, v34, v35, vcc
	v_pk_mul_f32 v[60:61], v[32:33], v[54:55] op_sel_hi:[1,0]
	v_pk_mul_f32 v[62:63], v[36:37], v[54:55] op_sel_hi:[1,0]
	global_load_dwordx4 v[32:35], v[64:65], off offset:16
	global_load_dwordx4 v[36:39], v[64:65], off
	v_pk_mul_f32 v[42:43], v[42:43], v[54:55] op_sel_hi:[1,0]
	v_pk_mul_f32 v[44:45], v[44:45], v[54:55] op_sel_hi:[1,0]
	s_waitcnt vmcnt(0)
	v_pk_mul_f32 v[32:33], v[32:33], v[42:43]
	v_lshl_add_u64 v[42:43], s[46:47], 0, v[58:59]
	v_pk_mul_f32 v[38:39], v[38:39], v[62:63]
	v_pk_mul_f32 v[36:37], v[36:37], v[60:61]
	v_pk_mul_f32 v[34:35], v[34:35], v[44:45]
	v_lshl_add_u64 v[44:45], v[140:141], 1, v[42:43]
	v_lshl_add_u64 v[42:43], v[56:57], 2, s[56:57]
	v_cvt_pk_bf16_f32 v58, v36, v37
	v_cvt_pk_bf16_f32 v59, v38, v39
	v_cvt_pk_bf16_f32 v60, v32, v33
	v_cvt_pk_bf16_f32 v61, v34, v35
	global_store_dwordx4 v[44:45], v[58:61], off
	s_and_saveexec_b64 s[0:1], s[10:11]
	s_cbranch_execz .LBB0_330
	v_lshl_add_u64 v[56:57], v[140:141], 2, v[42:43]
	v_lshl_add_u64 v[58:59], v[56:57], 0, s[70:71]
	v_add_co_u32_e32 v56, vcc, 0x2108000, v56
	s_nop 1
	v_addc_co_u32_e32 v57, vcc, 0, v57, vcc
	global_store_dwordx4 v[56:57], v[36:39], off
	global_store_dwordx4 v[58:59], v[32:35], off offset:16

; __device__ __forceinline__ float gelu_tanh(float x) { const float u = 1.5957691216f * (x + 0.044715f * x * x * x); return x * __builtin_amdgcn_rcpf(1.f + __expf(-u)); }
; __device__ __forceinline__ void st_bf16x8(bf16_t* p, const f32x4 a, const f32x4 b) { uint4 o; o.x = cvt_pk_bf16(a[0], a[1]); o.y = cvt_pk_bf16(a[2], a[3]); o.z = cvt_pk_bf16(b[0], b[1]); o.w = cvt_pk_bf16(b[2], b[3]); *(uint4*)p = o; }
;     __device__ __forceinline__ void row(const f32x4 (&a)[2][2], int row, int pn, int wc, int fq) const {
;         if (pn < 2 || pn == 4 || pn == 5) {
;             bf16_t* dst = (pn < 2 ? pU : pBG) + (size_t)row * 512 + (pn & 1) * 256 + wc * 32 + 8 * fq;
; #pragma unroll
;             for (int bj = 0; bj < 2; ++bj) { f32x4 v0 = a[bj][0], v1 = a[bj][1];
;                 if (pn < 2) {
; #pragma unroll
;                     for (int j = 0; j < 4; ++j) { v0[j] = gelu_tanh(v0[j]); v1[j] = gelu_tanh(v1[j]); } }
;                 st_bf16x8(dst + bj * HALF, v0, v1); }
.LBB0_334:
	s_and_b64 vcc, exec, s[4:5]
	s_cbranch_vccnz .LBB0_336
	v_mov_b32_e32 v190, 0x3d372713
	v_mov_b32_e32 v192, 0xbfcc422a
	v_mov_b32_e32 v194, 0x3fb8aa3b
	v_pk_mul_f32 v[196:197], v[24:25], v[190:191] op_sel_hi:[1,0]
	v_pk_mul_f32 v[198:199], v[26:27], v[190:191] op_sel_hi:[1,0]
	v_pk_mul_f32 v[200:201], v[28:29], v[190:191] op_sel_hi:[1,0]
	v_pk_mul_f32 v[202:203], v[30:31], v[190:191] op_sel_hi:[1,0]
	v_pk_mul_f32 v[196:197], v[24:25], v[196:197]
	v_pk_mul_f32 v[198:199], v[26:27], v[198:199]
	v_pk_mul_f32 v[200:201], v[28:29], v[200:201]
	v_pk_mul_f32 v[202:203], v[30:31], v[202:203]
	v_pk_fma_f32 v[196:197], v[24:25], v[196:197], v[24:25]
	v_pk_fma_f32 v[198:199], v[26:27], v[198:199], v[26:27]
	v_pk_fma_f32 v[200:201], v[28:29], v[200:201], v[28:29]
	v_pk_fma_f32 v[202:203], v[30:31], v[202:203], v[30:31]
	v_pk_mul_f32 v[196:197], v[196:197], v[192:193] op_sel_hi:[1,0]
	v_pk_mul_f32 v[198:199], v[198:199], v[192:193] op_sel_hi:[1,0]
	v_pk_mul_f32 v[200:201], v[200:201], v[192:193] op_sel_hi:[1,0]
	v_pk_mul_f32 v[202:203], v[202:203], v[192:193] op_sel_hi:[1,0]
	v_pk_mul_f32 v[196:197], v[196:197], v[194:195] op_sel_hi:[1,0]
	v_pk_mul_f32 v[198:199], v[198:199], v[194:195] op_sel_hi:[1,0]
	v_pk_mul_f32 v[200:201], v[200:201], v[194:195] op_sel_hi:[1,0]
	v_pk_mul_f32 v[202:203], v[202:203], v[194:195] op_sel_hi:[1,0]
	v_exp_f32_e32 v196, v196
	v_exp_f32_e32 v197, v197
	v_exp_f32_e32 v198, v198
	v_exp_f32_e32 v199, v199
	v_exp_f32_e32 v200, v200
	v_exp_f32_e32 v201, v201
	v_exp_f32_e32 v202, v202
	v_exp_f32_e32 v203, v203
	v_pk_add_f32 v[196:197], v[196:197], 1.0 op_sel_hi:[1,0]
	v_pk_add_f32 v[198:199], v[198:199], 1.0 op_sel_hi:[1,0]
	v_pk_add_f32 v[200:201], v[200:201], 1.0 op_sel_hi:[1,0]
	v_pk_add_f32 v[202:203], v[202:203], 1.0 op_sel_hi:[1,0]
	v_rcp_f32_e32 v196, v196
	v_rcp_f32_e32 v197, v197
	v_rcp_f32_e32 v198, v198
	v_rcp_f32_e32 v199, v199
	v_rcp_f32_e32 v200, v200
	v_rcp_f32_e32 v201, v201
	v_rcp_f32_e32 v202, v202
	v_rcp_f32_e32 v203, v203
	v_pk_mul_f32 v[24:25], v[24:25], v[196:197]
	v_pk_mul_f32 v[26:27], v[26:27], v[198:199]
	v_pk_mul_f32 v[28:29], v[28:29], v[200:201]
	v_pk_mul_f32 v[30:31], v[30:31], v[202:203]
	s_nop 0
	s_nop 0
	s_nop 0
	s_nop 0
.LBB0_336:
	s_and_b64 s[0:1], s[80:81], exec
	v_ashrrev_i32_e32 v41, 31, v40
	s_cselect_b32 s1, s31, s49
	s_cselect_b32 s0, s30, s48
	v_lshlrev_b64 v[32:33], 10, v[40:41]
	v_lshl_add_u64 v[32:33], s[0:1], 0, v[32:33]
	s_lshl_b32 s64, s61, 1
	v_lshl_add_u64 v[32:33], v[32:33], 0, s[64:65]
	s_lshl_b32 s64, s91, 1
	v_lshl_add_u64 v[32:33], v[32:33], 0, s[64:65]
	v_lshlrev_b32_e32 v34, 1, v142
	v_mov_b32_e32 v35, v141
	v_lshl_add_u64 v[32:33], v[32:33], 0, v[34:35]
	s_and_b64 vcc, exec, s[4:5]
	v_cvt_pk_bf16_f32 v28, v28, v29
	v_cvt_pk_bf16_f32 v29, v30, v31
	v_cvt_pk_bf16_f32 v30, v24, v25
	v_cvt_pk_bf16_f32 v31, v26, v27
	global_store_dwordx4 v[32:33], v[28:31], off
	s_cbranch_vccnz .LBB0_338
	v_mov_b32_e32 v190, 0x3d372713
	v_mov_b32_e32 v192, 0xbfcc422a
	v_mov_b32_e32 v194, 0x3fb8aa3b
	v_pk_mul_f32 v[196:197], v[16:17], v[190:191] op_sel_hi:[1,0]
	v_pk_mul_f32 v[198:199], v[18:19], v[190:191] op_sel_hi:[1,0]
	v_pk_mul_f32 v[200:201], v[20:21], v[190:191] op_sel_hi:[1,0]
	v_pk_mul_f32 v[202:203], v[22:23], v[190:191] op_sel_hi:[1,0]
	v_pk_mul_f32 v[196:197], v[16:17], v[196:197]
	v_pk_mul_f32 v[198:199], v[18:19], v[198:199]
	v_pk_mul_f32 v[200:201], v[20:21], v[200:201]
	v_pk_mul_f32 v[202:203], v[22:23], v[202:203]
	v_pk_fma_f32 v[196:197], v[16:17], v[196:197], v[16:17]
	v_pk_fma_f32 v[198:199], v[18:19], v[198:199], v[18:19]
	v_pk_fma_f32 v[200:201], v[20:21], v[200:201], v[20:21]
	v_pk_fma_f32 v[202:203], v[22:23], v[202:203], v[22:23]
	v_pk_mul_f32 v[196:197], v[196:197], v[192:193] op_sel_hi:[1,0]
	v_pk_mul_f32 v[198:199], v[198:199], v[192:193] op_sel_hi:[1,0]
	v_pk_mul_f32 v[200:201], v[200:201], v[192:193] op_sel_hi:[1,0]
	v_pk_mul_f32 v[202:203], v[202:203], v[192:193] op_sel_hi:[1,0]
	v_pk_mul_f32 v[196:197], v[196:197], v[194:195] op_sel_hi:[1,0]
	v_pk_mul_f32 v[198:199], v[198:199], v[194:195] op_sel_hi:[1,0]
	v_pk_mul_f32 v[200:201], v[200:201], v[194:195] op_sel_hi:[1,0]
	v_pk_mul_f32 v[202:203], v[202:203], v[194:195] op_sel_hi:[1,0]
	v_exp_f32_e32 v196, v196
	v_exp_f32_e32 v197, v197
	v_exp_f32_e32 v198, v198
	v_exp_f32_e32 v199, v199
	v_exp_f32_e32 v200, v200
	v_exp_f32_e32 v201, v201
	v_exp_f32_e32 v202, v202
	v_exp_f32_e32 v203, v203
	v_pk_add_f32 v[196:197], v[196:197], 1.0 op_sel_hi:[1,0]
	v_pk_add_f32 v[198:199], v[198:199], 1.0 op_sel_hi:[1,0]
	v_pk_add_f32 v[200:201], v[200:201], 1.0 op_sel_hi:[1,0]
	v_pk_add_f32 v[202:203], v[202:203], 1.0 op_sel_hi:[1,0]
	v_rcp_f32_e32 v196, v196
	v_rcp_f32_e32 v197, v197
	v_rcp_f32_e32 v198, v198
	v_rcp_f32_e32 v199, v199
	v_rcp_f32_e32 v200, v200
	v_rcp_f32_e32 v201, v201
	v_rcp_f32_e32 v202, v202
	v_rcp_f32_e32 v203, v203
	v_pk_mul_f32 v[16:17], v[16:17], v[196:197]
	v_pk_mul_f32 v[18:19], v[18:19], v[198:199]
	v_pk_mul_f32 v[20:21], v[20:21], v[200:201]
	v_pk_mul_f32 v[22:23], v[22:23], v[202:203]
	s_nop 0
	s_nop 0
	s_nop 0
	s_nop 0

; __device__ __forceinline__ float gelu_tanh(float x) { const float u = 1.5957691216f * (x + 0.044715f * x * x * x); return x * __builtin_amdgcn_rcpf(1.f + __expf(-u)); }
; __device__ __forceinline__ void st_bf16x8(bf16_t* p, const f32x4 a, const f32x4 b) { uint4 o; o.x = cvt_pk_bf16(a[0], a[1]); o.y = cvt_pk_bf16(a[2], a[3]); o.z = cvt_pk_bf16(b[0], b[1]); o.w = cvt_pk_bf16(b[2], b[3]); *(uint4*)p = o; }
;     __device__ __forceinline__ void row(const f32x4 (&a)[2][2], int row, int pn, int wc, int fq) const {
;     ...
;             const int head = (pn - 2) * 4 + wc;
;             f32x4 g[2][2]; float ss = 0.f;
; #pragma unroll
;             for (int bj = 0; bj < 2; ++bj)
; #pragma unroll
;                 for (int n = 0; n < 2; ++n)
; #pragma unroll
;                     for (int j = 0; j < 4; ++j) { const float t = gelu_tanh(a[bj][n][j]); g[bj][n][j] = t; ss += t * t; }
;             ss += __shfl_xor(ss, 16); ss += __shfl_xor(ss, 32);
;             const float rs = rsqrtf(ss * (1.f / 64.f) + EPS);
; #pragma unroll
;             for (int bj = 0; bj < 2; ++bj) { const int d = head * 64 + bj * 32 + 8 * fq;
;                 const f32x4 v0 = g[bj][0] * rs * *(const f32x4*)(g_v + d), v1 = g[bj][1] * rs * *(const f32x4*)(g_v + d + 4);
;                 st_bf16x8(pV + (size_t)row * 512 + d, v0, v1);
;                 if (row >= NP && row < NTOK) { float* o = out + O_VS + (size_t)(row - NP) * 512 + d; *(f32x4*)o = v0; *(f32x4*)(o + 4) = v1; } }
.LBB0_345:
	s_and_b64 vcc, exec, s[0:1]
	s_cbranch_vccz .LBB0_351
	v_mov_b32_e32 v190, 0x3d372713
	v_mov_b32_e32 v192, 0xbfcc422a
	v_mov_b32_e32 v194, 0x3fb8aa3b
	v_pk_mul_f32 v[16:17], v[12:13], v[190:191] op_sel_hi:[1,0]
	v_pk_mul_f32 v[20:21], v[14:15], v[190:191] op_sel_hi:[1,0]
	v_pk_mul_f32 v[26:27], v[8:9], v[190:191] op_sel_hi:[1,0]
	v_pk_mul_f32 v[28:29], v[10:11], v[190:191] op_sel_hi:[1,0]
	v_pk_mul_f32 v[30:31], v[4:5], v[190:191] op_sel_hi:[1,0]
	v_pk_mul_f32 v[32:33], v[6:7], v[190:191] op_sel_hi:[1,0]
	v_pk_mul_f32 v[34:35], v[0:1], v[190:191] op_sel_hi:[1,0]
	v_pk_mul_f32 v[36:37], v[2:3], v[190:191] op_sel_hi:[1,0]
	v_pk_mul_f32 v[16:17], v[12:13], v[16:17]
	v_pk_mul_f32 v[20:21], v[14:15], v[20:21]
	v_pk_mul_f32 v[26:27], v[8:9], v[26:27]
	v_pk_mul_f32 v[28:29], v[10:11], v[28:29]
	v_pk_mul_f32 v[30:31], v[4:5], v[30:31]
	v_pk_mul_f32 v[32:33], v[6:7], v[32:33]
	v_pk_mul_f32 v[34:35], v[0:1], v[34:35]
	v_pk_mul_f32 v[36:37], v[2:3], v[36:37]
	v_pk_fma_f32 v[16:17], v[12:13], v[16:17], v[12:13]
	v_pk_fma_f32 v[20:21], v[14:15], v[20:21], v[14:15]
	v_pk_fma_f32 v[26:27], v[8:9], v[26:27], v[8:9]
	v_pk_fma_f32 v[28:29], v[10:11], v[28:29], v[10:11]
	v_pk_fma_f32 v[30:31], v[4:5], v[30:31], v[4:5]
	v_pk_fma_f32 v[32:33], v[6:7], v[32:33], v[6:7]
	v_pk_fma_f32 v[34:35], v[0:1], v[34:35], v[0:1]
	v_pk_fma_f32 v[36:37], v[2:3], v[36:37], v[2:3]
	v_pk_mul_f32 v[16:17], v[16:17], v[192:193] op_sel_hi:[1,0]
	v_pk_mul_f32 v[20:21], v[20:21], v[192:193] op_sel_hi:[1,0]
	v_pk_mul_f32 v[26:27], v[26:27], v[192:193] op_sel_hi:[1,0]
	v_pk_mul_f32 v[28:29], v[28:29], v[192:193] op_sel_hi:[1,0]
	v_pk_mul_f32 v[30:31], v[30:31], v[192:193] op_sel_hi:[1,0]
	v_pk_mul_f32 v[32:33], v[32:33], v[192:193] op_sel_hi:[1,0]
	v_pk_mul_f32 v[34:35], v[34:35], v[192:193] op_sel_hi:[1,0]
	v_pk_mul_f32 v[36:37], v[36:37], v[192:193] op_sel_hi:[1,0]
	v_pk_mul_f32 v[16:17], v[16:17], v[194:195] op_sel_hi:[1,0]
	v_pk_mul_f32 v[20:21], v[20:21], v[194:195] op_sel_hi:[1,0]
	v_pk_mul_f32 v[26:27], v[26:27], v[194:195] op_sel_hi:[1,0]
	v_pk_mul_f32 v[28:29], v[28:29], v[194:195] op_sel_hi:[1,0]
	v_pk_mul_f32 v[30:31], v[30:31], v[194:195] op_sel_hi:[1,0]
	v_pk_mul_f32 v[32:33], v[32:33], v[194:195] op_sel_hi:[1,0]
	v_pk_mul_f32 v[34:35], v[34:35], v[194:195] op_sel_hi:[1,0]
	v_pk_mul_f32 v[36:37], v[36:37], v[194:195] op_sel_hi:[1,0]
	v_exp_f32_e32 v16, v16
	v_exp_f32_e32 v17, v17
	v_exp_f32_e32 v20, v20
	v_exp_f32_e32 v21, v21
	v_exp_f32_e32 v26, v26
	v_exp_f32_e32 v27, v27
	v_exp_f32_e32 v28, v28
	v_exp_f32_e32 v29, v29
	v_exp_f32_e32 v30, v30
	v_exp_f32_e32 v31, v31
	v_exp_f32_e32 v32, v32
	v_exp_f32_e32 v33, v33
	v_exp_f32_e32 v34, v34
	v_exp_f32_e32 v35, v35
	v_exp_f32_e32 v36, v36
	v_exp_f32_e32 v37, v37
	v_pk_add_f32 v[16:17], v[16:17], 1.0 op_sel_hi:[1,0]
	v_pk_add_f32 v[20:21], v[20:21], 1.0 op_sel_hi:[1,0]
	v_pk_add_f32 v[26:27], v[26:27], 1.0 op_sel_hi:[1,0]
	v_pk_add_f32 v[28:29], v[28:29], 1.0 op_sel_hi:[1,0]
	v_pk_add_f32 v[30:31], v[30:31], 1.0 op_sel_hi:[1,0]
	v_pk_add_f32 v[32:33], v[32:33], 1.0 op_sel_hi:[1,0]
	v_pk_add_f32 v[34:35], v[34:35], 1.0 op_sel_hi:[1,0]
	v_pk_add_f32 v[36:37], v[36:37], 1.0 op_sel_hi:[1,0]
	v_rcp_f32_e32 v16, v16
	v_rcp_f32_e32 v17, v17
	v_rcp_f32_e32 v20, v20
	v_rcp_f32_e32 v21, v21
	v_rcp_f32_e32 v26, v26
	v_rcp_f32_e32 v27, v27
	v_rcp_f32_e32 v28, v28
	v_rcp_f32_e32 v29, v29
	v_rcp_f32_e32 v30, v30
	v_rcp_f32_e32 v31, v31
	v_rcp_f32_e32 v32, v32
	v_rcp_f32_e32 v33, v33
	v_rcp_f32_e32 v34, v34
	v_rcp_f32_e32 v35, v35
	v_rcp_f32_e32 v36, v36
	v_rcp_f32_e32 v37, v37
	v_pk_mul_f32 v[16:17], v[12:13], v[16:17]
	v_pk_mul_f32 v[20:21], v[14:15], v[20:21]
	v_pk_mul_f32 v[26:27], v[8:9], v[26:27]
	v_pk_mul_f32 v[28:29], v[10:11], v[28:29]
	v_pk_mul_f32 v[30:31], v[4:5], v[30:31]
	v_pk_mul_f32 v[32:33], v[6:7], v[32:33]
	v_pk_mul_f32 v[34:35], v[0:1], v[34:35]
	v_pk_mul_f32 v[36:37], v[2:3], v[36:37]
	v_pk_mul_f32 v[18:19], v[16:17], v[16:17]
	v_pk_mul_f32 v[22:23], v[20:21], v[20:21]
	v_add_f32_e32 v18, v18, v19
	v_add_f32_e32 v18, v22, v18
	v_pk_mul_f32 v[38:39], v[26:27], v[26:27]
	v_add_f32_e32 v18, v23, v18
	v_add_f32_e32 v18, v38, v18
	v_pk_mul_f32 v[40:41], v[28:29], v[28:29]
	v_add_f32_e32 v18, v39, v18
	v_add_f32_e32 v18, v40, v18
	v_pk_mul_f32 v[42:43], v[30:31], v[30:31]
	v_add_f32_e32 v18, v41, v18
	v_add_f32_e32 v18, v18, v42
	v_pk_mul_f32 v[44:45], v[32:33], v[32:33]
	v_add_f32_e32 v18, v43, v18
	v_add_f32_e32 v18, v44, v18
	v_pk_mul_f32 v[46:47], v[34:35], v[34:35]
	v_add_f32_e32 v18, v45, v18
	v_add_f32_e32 v18, v46, v18
	v_pk_mul_f32 v[48:49], v[36:37], v[36:37]
	v_add_f32_e32 v18, v47, v18
	v_add_f32_e32 v18, v48, v18
	v_add_f32_e32 v18, v49, v18
	ds_bpermute_b32 v19, v229, v18
	v_lshl_add_u64 v[48:49], v[140:141], 2, s[18:19]
	v_ashrrev_i32_e32 v25, 31, v24
	v_lshlrev_b64 v[42:43], 10, v[24:25]
	v_lshlrev_b32_e32 v40, 9, v24
	s_waitcnt lgkmcnt(0)
	v_add_f32_e32 v18, v18, v19
	ds_bpermute_b32 v19, v230, v18
	v_mov_b32_e32 v41, v141
	s_waitcnt lgkmcnt(0)
	v_add_f32_e32 v18, v18, v19
	v_fmamk_f32 v18, v18, 0x3c800000, v188
	v_cmp_gt_f32_e32 vcc, s13, v18
	v_mul_f32_e32 v19, 0x4b800000, v18
	s_nop 0
	v_cndmask_b32_e32 v18, v18, v19, vcc
	v_rsq_f32_e32 v18, v18
	s_nop 0
	v_mul_f32_e32 v19, 0x45800000, v18
	v_cndmask_b32_e32 v38, v18, v19, vcc
	v_pk_mul_f32 v[44:45], v[16:17], v[38:39] op_sel_hi:[1,0]
	v_pk_mul_f32 v[46:47], v[20:21], v[38:39] op_sel_hi:[1,0]
	global_load_dwordx4 v[16:19], v[48:49], off offset:16
	global_load_dwordx4 v[20:23], v[48:49], off
	v_pk_mul_f32 v[26:27], v[26:27], v[38:39] op_sel_hi:[1,0]
	v_pk_mul_f32 v[28:29], v[28:29], v[38:39] op_sel_hi:[1,0]
	s_waitcnt vmcnt(0)
	v_pk_mul_f32 v[16:17], v[16:17], v[26:27]
	v_lshl_add_u64 v[26:27], s[46:47], 0, v[42:43]
	v_pk_mul_f32 v[22:23], v[22:23], v[46:47]
	v_pk_mul_f32 v[20:21], v[20:21], v[44:45]
	v_pk_mul_f32 v[18:19], v[18:19], v[28:29]
	v_lshl_add_u64 v[28:29], v[140:141], 1, v[26:27]
	v_lshl_add_u64 v[26:27], v[40:41], 2, s[56:57]
	v_cvt_pk_bf16_f32 v42, v20, v21
	v_cvt_pk_bf16_f32 v43, v22, v23
	v_cvt_pk_bf16_f32 v44, v16, v17
	v_cvt_pk_bf16_f32 v45, v18, v19
	global_store_dwordx4 v[28:29], v[42:45], off
	s_and_saveexec_b64 s[0:1], s[10:11]
	s_cbranch_execz .LBB0_348
	v_lshl_add_u64 v[40:41], v[140:141], 2, v[26:27]
	v_lshl_add_u64 v[42:43], v[40:41], 0, s[70:71]
	v_add_co_u32_e32 v40, vcc, 0x2108000, v40
	s_nop 1
	v_addc_co_u32_e32 v41, vcc, 0, v41, vcc
	global_store_dwordx4 v[40:41], v[20:23], off
	global_store_dwordx4 v[42:43], v[16:19], off offset:16

; __device__ __forceinline__ float gelu_tanh(float x) { const float u = 1.5957691216f * (x + 0.044715f * x * x * x); return x * __builtin_amdgcn_rcpf(1.f + __expf(-u)); }
; __device__ __forceinline__ void st_bf16x8(bf16_t* p, const f32x4 a, const f32x4 b) { uint4 o; o.x = cvt_pk_bf16(a[0], a[1]); o.y = cvt_pk_bf16(a[2], a[3]); o.z = cvt_pk_bf16(b[0], b[1]); o.w = cvt_pk_bf16(b[2], b[3]); *(uint4*)p = o; }
;     __device__ __forceinline__ void row(const f32x4 (&a)[2][2], int row, int pn, int wc, int fq) const {
;         if (pn < 2 || pn == 4 || pn == 5) {
;             bf16_t* dst = (pn < 2 ? pU : pBG) + (size_t)row * 512 + (pn & 1) * 256 + wc * 32 + 8 * fq;
; #pragma unroll
;             for (int bj = 0; bj < 2; ++bj) { f32x4 v0 = a[bj][0], v1 = a[bj][1];
;                 if (pn < 2) {
; #pragma unroll
;                     for (int j = 0; j < 4; ++j) { v0[j] = gelu_tanh(v0[j]); v1[j] = gelu_tanh(v1[j]); } }
;                 st_bf16x8(dst + bj * HALF, v0, v1); }
.LBB0_352:
	s_and_b64 vcc, exec, s[4:5]
	s_cbranch_vccnz .LBB0_354
	v_mov_b32_e32 v190, 0x3d372713
	v_mov_b32_e32 v192, 0xbfcc422a
	v_mov_b32_e32 v194, 0x3fb8aa3b
	v_pk_mul_f32 v[196:197], v[8:9], v[190:191] op_sel_hi:[1,0]
	v_pk_mul_f32 v[198:199], v[10:11], v[190:191] op_sel_hi:[1,0]
	v_pk_mul_f32 v[200:201], v[12:13], v[190:191] op_sel_hi:[1,0]
	v_pk_mul_f32 v[202:203], v[14:15], v[190:191] op_sel_hi:[1,0]
	v_pk_mul_f32 v[196:197], v[8:9], v[196:197]
	v_pk_mul_f32 v[198:199], v[10:11], v[198:199]
	v_pk_mul_f32 v[200:201], v[12:13], v[200:201]
	v_pk_mul_f32 v[202:203], v[14:15], v[202:203]
	v_pk_fma_f32 v[196:197], v[8:9], v[196:197], v[8:9]
	v_pk_fma_f32 v[198:199], v[10:11], v[198:199], v[10:11]
	v_pk_fma_f32 v[200:201], v[12:13], v[200:201], v[12:13]
	v_pk_fma_f32 v[202:203], v[14:15], v[202:203], v[14:15]
	v_pk_mul_f32 v[196:197], v[196:197], v[192:193] op_sel_hi:[1,0]
	v_pk_mul_f32 v[198:199], v[198:199], v[192:193] op_sel_hi:[1,0]
	v_pk_mul_f32 v[200:201], v[200:201], v[192:193] op_sel_hi:[1,0]
	v_pk_mul_f32 v[202:203], v[202:203], v[192:193] op_sel_hi:[1,0]
	v_pk_mul_f32 v[196:197], v[196:197], v[194:195] op_sel_hi:[1,0]
	v_pk_mul_f32 v[198:199], v[198:199], v[194:195] op_sel_hi:[1,0]
	v_pk_mul_f32 v[200:201], v[200:201], v[194:195] op_sel_hi:[1,0]
	v_pk_mul_f32 v[202:203], v[202:203], v[194:195] op_sel_hi:[1,0]
	v_exp_f32_e32 v196, v196
	v_exp_f32_e32 v197, v197
	v_exp_f32_e32 v198, v198
	v_exp_f32_e32 v199, v199
	v_exp_f32_e32 v200, v200
	v_exp_f32_e32 v201, v201
	v_exp_f32_e32 v202, v202
	v_exp_f32_e32 v203, v203
	v_pk_add_f32 v[196:197], v[196:197], 1.0 op_sel_hi:[1,0]
	v_pk_add_f32 v[198:199], v[198:199], 1.0 op_sel_hi:[1,0]
	v_pk_add_f32 v[200:201], v[200:201], 1.0 op_sel_hi:[1,0]
	v_pk_add_f32 v[202:203], v[202:203], 1.0 op_sel_hi:[1,0]
	v_rcp_f32_e32 v196, v196
	v_rcp_f32_e32 v197, v197
	v_rcp_f32_e32 v198, v198
	v_rcp_f32_e32 v199, v199
	v_rcp_f32_e32 v200, v200
	v_rcp_f32_e32 v201, v201
	v_rcp_f32_e32 v202, v202
	v_rcp_f32_e32 v203, v203
	v_pk_mul_f32 v[8:9], v[8:9], v[196:197]
	v_pk_mul_f32 v[10:11], v[10:11], v[198:199]
	v_pk_mul_f32 v[12:13], v[12:13], v[200:201]
	v_pk_mul_f32 v[14:15], v[14:15], v[202:203]
.LBB0_354:
	s_and_b64 s[0:1], s[80:81], exec
	v_ashrrev_i32_e32 v25, 31, v24
	s_cselect_b32 s1, s31, s49
	s_cselect_b32 s0, s30, s48
	v_lshlrev_b64 v[16:17], 10, v[24:25]
	v_lshl_add_u64 v[16:17], s[0:1], 0, v[16:17]
	s_lshl_b32 s64, s61, 1
	v_lshl_add_u64 v[16:17], v[16:17], 0, s[64:65]
	s_lshl_b32 s64, s91, 1
	v_lshl_add_u64 v[16:17], v[16:17], 0, s[64:65]
	v_lshlrev_b32_e32 v140, 1, v142
	v_lshl_add_u64 v[16:17], v[16:17], 0, v[140:141]
	s_and_b64 vcc, exec, s[4:5]
	v_cvt_pk_bf16_f32 v12, v12, v13
	v_cvt_pk_bf16_f32 v13, v14, v15
	v_cvt_pk_bf16_f32 v14, v8, v9
	v_cvt_pk_bf16_f32 v15, v10, v11
	global_store_dwordx4 v[16:17], v[12:15], off
	s_cbranch_vccnz .LBB0_207
	v_mov_b32_e32 v190, 0x3d372713
	v_mov_b32_e32 v192, 0xbfcc422a
	v_mov_b32_e32 v194, 0x3fb8aa3b
	v_pk_mul_f32 v[196:197], v[0:1], v[190:191] op_sel_hi:[1,0]
	v_pk_mul_f32 v[198:199], v[2:3], v[190:191] op_sel_hi:[1,0]
	v_pk_mul_f32 v[200:201], v[4:5], v[190:191] op_sel_hi:[1,0]
	v_pk_mul_f32 v[202:203], v[6:7], v[190:191] op_sel_hi:[1,0]
	v_pk_mul_f32 v[196:197], v[0:1], v[196:197]
	v_pk_mul_f32 v[198:199], v[2:3], v[198:199]
	v_pk_mul_f32 v[200:201], v[4:5], v[200:201]
	v_pk_mul_f32 v[202:203], v[6:7], v[202:203]
	v_pk_fma_f32 v[196:197], v[0:1], v[196:197], v[0:1]
	v_pk_fma_f32 v[198:199], v[2:3], v[198:199], v[2:3]
	v_pk_fma_f32 v[200:201], v[4:5], v[200:201], v[4:5]
	v_pk_fma_f32 v[202:203], v[6:7], v[202:203], v[6:7]
	v_pk_mul_f32 v[196:197], v[196:197], v[192:193] op_sel_hi:[1,0]
	v_pk_mul_f32 v[198:199], v[198:199], v[192:193] op_sel_hi:[1,0]
	v_pk_mul_f32 v[200:201], v[200:201], v[192:193] op_sel_hi:[1,0]
	v_pk_mul_f32 v[202:203], v[202:203], v[192:193] op_sel_hi:[1,0]
	v_pk_mul_f32 v[196:197], v[196:197], v[194:195] op_sel_hi:[1,0]
	v_pk_mul_f32 v[198:199], v[198:199], v[194:195] op_sel_hi:[1,0]
	v_pk_mul_f32 v[200:201], v[200:201], v[194:195] op_sel_hi:[1,0]
	v_pk_mul_f32 v[202:203], v[202:203], v[194:195] op_sel_hi:[1,0]
	v_exp_f32_e32 v196, v196
	v_exp_f32_e32 v197, v197
	v_exp_f32_e32 v198, v198
	v_exp_f32_e32 v199, v199
	v_exp_f32_e32 v200, v200
	v_exp_f32_e32 v201, v201
	v_exp_f32_e32 v202, v202
	v_exp_f32_e32 v203, v203
	v_pk_add_f32 v[196:197], v[196:197], 1.0 op_sel_hi:[1,0]
	v_pk_add_f32 v[198:199], v[198:199], 1.0 op_sel_hi:[1,0]
	v_pk_add_f32 v[200:201], v[200:201], 1.0 op_sel_hi:[1,0]
	v_pk_add_f32 v[202:203], v[202:203], 1.0 op_sel_hi:[1,0]
	v_rcp_f32_e32 v196, v196
	v_rcp_f32_e32 v197, v197
	v_rcp_f32_e32 v198, v198
	v_rcp_f32_e32 v199, v199
	v_rcp_f32_e32 v200, v200
	v_rcp_f32_e32 v201, v201
	v_rcp_f32_e32 v202, v202
	v_rcp_f32_e32 v203, v203
	v_pk_mul_f32 v[0:1], v[0:1], v[196:197]
	v_pk_mul_f32 v[2:3], v[2:3], v[198:199]
	v_pk_mul_f32 v[4:5], v[4:5], v[200:201]
	v_pk_mul_f32 v[6:7], v[6:7], v[202:203]
	s_branch .LBB0_207
